# code placement variant 2: up-GEMM loop at 48, residual loop at 0, NA window loop at 48 (mod 64)
# baseline (speedup 1.0000x reference)
; #define PG8_STAGE(bufoff, gbase, voff) do { _Pragma("unroll") for (int _i = 0; _i < 2; ++_i) \
;         __builtin_amdgcn_global_load_lds((const unsigned*)((const char*)(gbase) + (voff)[_i]), (PG8_LAS unsigned*)(lds + (bufoff) + ldsw + _i * 8192), 16, 0, 0); } while (0)
; #define PG8_LDA(dst, b, h) do { _Pragma("unroll") for (int m = 0; m < 4; ++m) _Pragma("unroll") for (int k = 0; k < 2; ++k) dst[m][k] = *(const PG8_LAS bf16x8*)(lds + PG8_SA(b, h) + aoff + m * 2048 + k * 1024); } while (0)
; #define PG8_LDB(dst, b, h) do { _Pragma("unroll") for (int n = 0; n < 2; ++n) _Pragma("unroll") for (int k = 0; k < 2; ++k) dst[n][k] = *(const PG8_LAS bf16x8*)(lds + PG8_SB(b, h) + boff + n * 2048 + k * 1024); } while (0)
; #define PG8_MMA(ai, bj, At, Bt) do { __builtin_amdgcn_s_setprio(1); _Pragma("unroll") for (int m = 0; m < 4; ++m) _Pragma("unroll") for (int n = 0; n < 2; ++n) _Pragma("unroll") for (int k = 0; k < 2; ++k) \
;         acc[ai][bj][m][n] = __builtin_amdgcn_mfma_f32_16x16x32_bf16(Bt[n][k], At[m][k], acc[ai][bj][m][n], 0, 0, 0); __builtin_amdgcn_s_setprio(0); } while (0)
; #define PG8_WAIT_V(n) asm volatile("s_waitcnt vmcnt(" #n ")" ::: "memory")
; template <class Epi, class Sched, bool ALIGN_EPI = false, bool SP2 = false>
; __device__ __forceinline__ void gemm_phase(PG8_LAS unsigned char* lds, const Gemm g, const Sched& S, const Epi& E) {
;     ...
;         const char* nA = has_next ? (const char*)g.A + (size_t)nxt.pm * tstep : cA; const char* nB = has_next ? (const char*)g.Bt + (size_t)nxt.pn * tstep : cB;
;         for (int t = 0; t < nt; t += 2) {
;             const bool last = (t == nt - 2);
;             const char* a1 = cA + (size_t)(t + 1) * kstep;
;             const char* a2 = last ? nA : cA + (size_t)(t + 2) * kstep; const char* b2 = last ? nB : cB + (size_t)(t + 2) * kstep;
;             const char* a3 = a2 + kstep; const char* b3 = b2 + kstep;
;             if (last && has_next) S.a_ready(nxt);
;             if constexpr (SP2) {
;             PG8_LDB(B0, 0, 0); PG8_LDB(B1, 0, 1); PG8_SCHED; PG8_LDA(At, 0, 0); PG8_STAGE(PG8_SA(1, 1), a1 + hstep, voffA);
;             PG8_WAIT_V(8); PG8_WAIT_L(0); PG8_BAR; PG8_MMA(0, 0, At, B0); PG8_MMA(0, 1, At, B1); PG8_BAR; PG8_SCHED;
;             PG8_LDA(At, 0, 1); PG8_STAGE(PG8_SB(0, 0), b2, voffB); PG8_STAGE(PG8_SB(0, 1), b2 + hstep, voffB); PG8_STAGE(PG8_SA(0, 0), a2, voffA);
.Lpeel_u:
	s_add_u32 s34, s30, 0xfffc0080
	s_addc_u32 s35, s31, -1
	s_add_i32 s71, 0, 0x10000
	s_cmp_eq_u32 s62, 12
	s_cselect_b32 s41, s21, s35
	s_cselect_b32 s40, s27, s34
	v_add_u32_e32 v155, s71, v145
	s_cselect_b32 s35, s19, s54
	s_cselect_b32 s34, s50, s52
	s_add_i32 s74, 0, 0x14000
	ds_read_b128 v[156:159], v155
	ds_read_b128 v[160:163], v155 offset:1024
	ds_read_b128 v[164:167], v155 offset:2048
	ds_read_b128 v[168:171], v155 offset:3072
	v_add_u32_e32 v155, s74, v145
	ds_read_b128 v[172:175], v155
	ds_read_b128 v[176:179], v155 offset:1024
	ds_read_b128 v[180:183], v155 offset:2048
	ds_read_b128 v[208:211], v155 offset:3072
	v_lshl_add_u64 v[202:203], s[30:31], 0, v[134:135]
	s_add_i32 m0, s29, 0xc000
	ds_read_b128 v[212:215], v154
	ds_read_b128 v[216:219], v154 offset:1024
	ds_read_b128 v[220:223], v154 offset:2048
	ds_read_b128 v[224:227], v154 offset:3072
	ds_read_b128 v[228:231], v154 offset:4096
	ds_read_b128 v[232:235], v154 offset:5120
	ds_read_b128 v[236:239], v154 offset:6144
	ds_read_b128 v[240:243], v154 offset:7168
	global_load_lds_dwordx4 v[202:203], off
	v_lshl_add_u64 v[202:203], s[30:31], 0, v[136:137]
	s_add_i32 m0, s29, 0xe000
	s_nop 0
	global_load_lds_dwordx4 v[202:203], off
	s_waitcnt vmcnt(8)
	s_waitcnt lgkmcnt(0)
	s_barrier
	s_setprio 1
	s_waitcnt lgkmcnt(0)
	v_mfma_f32_16x16x32_bf16 v[126:129], v[156:159], v[212:215], 0
	v_mfma_f32_16x16x32_bf16 v[122:125], v[164:167], v[212:215], 0
	v_mfma_f32_16x16x32_bf16 v[110:113], v[156:159], v[220:223], 0
	v_mfma_f32_16x16x32_bf16 v[106:109], v[164:167], v[220:223], 0
	v_mfma_f32_16x16x32_bf16 v[94:97], v[156:159], v[228:231], 0
	v_mfma_f32_16x16x32_bf16 v[90:93], v[164:167], v[228:231], 0
	v_mfma_f32_16x16x32_bf16 v[78:81], v[156:159], v[236:239], 0
	v_mfma_f32_16x16x32_bf16 v[74:77], v[164:167], v[236:239], 0
	v_mfma_f32_16x16x32_bf16 v[126:129], v[160:163], v[216:219], v[126:129]
	v_mfma_f32_16x16x32_bf16 v[122:125], v[168:171], v[216:219], v[122:125]
	v_mfma_f32_16x16x32_bf16 v[110:113], v[160:163], v[224:227], v[110:113]
	v_mfma_f32_16x16x32_bf16 v[106:109], v[168:171], v[224:227], v[106:109]
	v_mfma_f32_16x16x32_bf16 v[94:97], v[160:163], v[232:235], v[94:97]
	v_mfma_f32_16x16x32_bf16 v[90:93], v[168:171], v[232:235], v[90:93]
	v_mfma_f32_16x16x32_bf16 v[78:81], v[160:163], v[240:243], v[78:81]
	v_mfma_f32_16x16x32_bf16 v[74:77], v[168:171], v[240:243], v[74:77]
	s_setprio 0
	s_setprio 1
	v_mfma_f32_16x16x32_bf16 v[118:121], v[172:175], v[212:215], 0
	v_mfma_f32_16x16x32_bf16 v[114:117], v[180:183], v[212:215], 0
	v_mfma_f32_16x16x32_bf16 v[102:105], v[172:175], v[220:223], 0
	v_mfma_f32_16x16x32_bf16 v[98:101], v[180:183], v[220:223], 0
	v_mfma_f32_16x16x32_bf16 v[86:89], v[172:175], v[228:231], 0
	v_mfma_f32_16x16x32_bf16 v[82:85], v[180:183], v[228:231], 0
	v_mfma_f32_16x16x32_bf16 v[70:73], v[172:175], v[236:239], 0
	v_mfma_f32_16x16x32_bf16 v[66:69], v[180:183], v[236:239], 0
	v_mfma_f32_16x16x32_bf16 v[118:121], v[176:179], v[216:219], v[118:121]
	v_mfma_f32_16x16x32_bf16 v[114:117], v[208:211], v[216:219], v[114:117]
	v_mfma_f32_16x16x32_bf16 v[102:105], v[176:179], v[224:227], v[102:105]
	v_mfma_f32_16x16x32_bf16 v[98:101], v[208:211], v[224:227], v[98:101]
	v_mfma_f32_16x16x32_bf16 v[86:89], v[176:179], v[232:235], v[86:89]
	v_mfma_f32_16x16x32_bf16 v[82:85], v[208:211], v[232:235], v[82:85]
	v_mfma_f32_16x16x32_bf16 v[70:73], v[176:179], v[240:243], v[70:73]
	v_mfma_f32_16x16x32_bf16 v[66:69], v[208:211], v[240:243], v[66:69]
	s_setprio 0
	s_barrier
	s_add_i32 s71, s71, s80
	v_lshl_add_u64 v[202:203], s[34:35], 0, v[132:133]
	s_mov_b32 m0, s71
	ds_read_b128 v[212:215], v154 offset:16384
	ds_read_b128 v[216:219], v154 offset:17408
	ds_read_b128 v[220:223], v154 offset:18432
	ds_read_b128 v[224:227], v154 offset:19456
	ds_read_b128 v[228:231], v154 offset:20480
	ds_read_b128 v[232:235], v154 offset:21504
	ds_read_b128 v[236:239], v154 offset:22528
	ds_read_b128 v[240:243], v154 offset:23552
	global_load_lds_dwordx4 v[202:203], off
	s_add_i32 m0, s71, 0x2000
	s_add_u32 s72, s34, 0x40000
	v_lshl_add_u64 v[204:205], s[34:35], 0, v[130:131]
	s_addc_u32 s73, s35, 0
	s_add_i32 s71, s74, s80
	global_load_lds_dwordx4 v[204:205], off
	v_lshl_add_u64 v[244:245], s[72:73], 0, v[132:133]
	s_mov_b32 m0, s71
	v_lshl_add_u64 v[246:247], s[40:41], 0, v[130:131]
	global_load_lds_dwordx4 v[244:245], off
	v_lshl_add_u64 v[244:245], s[72:73], 0, v[130:131]
	s_add_i32 m0, s71, 0x2000
	s_nop 0
	global_load_lds_dwordx4 v[244:245], off
	v_lshl_add_u64 v[244:245], s[40:41], 0, v[132:133]
	s_mov_b32 m0, s29
	s_nop 0
	global_load_lds_dwordx4 v[244:245], off
	s_mov_b32 m0, s81
	s_nop 0
	global_load_lds_dwordx4 v[246:247], off
	s_waitcnt vmcnt(8)
	s_waitcnt lgkmcnt(0)
	s_barrier
; #define PG8_STAGE(bufoff, gbase, voff) do { _Pragma("unroll") for (int _i = 0; _i < 2; ++_i) \
;         __builtin_amdgcn_global_load_lds((const unsigned*)((const char*)(gbase) + (voff)[_i]), (PG8_LAS unsigned*)(lds + (bufoff) + ldsw + _i * 8192), 16, 0, 0); } while (0)
; #define PG8_LDA(dst, b, h) do { _Pragma("unroll") for (int m = 0; m < 4; ++m) _Pragma("unroll") for (int k = 0; k < 2; ++k) dst[m][k] = *(const PG8_LAS bf16x8*)(lds + PG8_SA(b, h) + aoff + m * 2048 + k * 1024); } while (0)
; #define PG8_LDB(dst, b, h) do { _Pragma("unroll") for (int n = 0; n < 2; ++n) _Pragma("unroll") for (int k = 0; k < 2; ++k) dst[n][k] = *(const PG8_LAS bf16x8*)(lds + PG8_SB(b, h) + boff + n * 2048 + k * 1024); } while (0)
; #define PG8_MMA(ai, bj, At, Bt) do { __builtin_amdgcn_s_setprio(1); _Pragma("unroll") for (int m = 0; m < 4; ++m) _Pragma("unroll") for (int n = 0; n < 2; ++n) _Pragma("unroll") for (int k = 0; k < 2; ++k) \
;         acc[ai][bj][m][n] = __builtin_amdgcn_mfma_f32_16x16x32_bf16(Bt[n][k], At[m][k], acc[ai][bj][m][n], 0, 0, 0); __builtin_amdgcn_s_setprio(0); } while (0)
; #define PG8_WAIT_V(n) asm volatile("s_waitcnt vmcnt(" #n ")" ::: "memory")
; #define PG8_WAIT_L(n) asm volatile("s_waitcnt lgkmcnt(" #n ")" ::: "memory")
; #define PG8_BAR __builtin_amdgcn_s_barrier()
; #define PG8_SCHED __builtin_amdgcn_sched_barrier(0)
; template <class Epi, class Sched, bool ALIGN_EPI = false, bool SP2 = false>
; __device__ __forceinline__ void gemm_phase(PG8_LAS unsigned char* lds, const Gemm g, const Sched& S, const Epi& E) {
;     ...
;             PG8_WAIT_V(8); PG8_WAIT_L(0); PG8_BAR; PG8_MMA(1, 0, At, B0); PG8_MMA(1, 1, At, B1); PG8_BAR; PG8_SCHED;
;             PG8_LDB(B0, 1, 0); PG8_LDB(B1, 1, 1); PG8_SCHED; PG8_LDA(At, 1, 0); PG8_STAGE(PG8_SA(0, 1), a2 + hstep, voffA);
;             PG8_WAIT_V(8); PG8_WAIT_L(0); PG8_BAR; PG8_MMA(0, 0, At, B0); PG8_MMA(0, 1, At, B1); PG8_BAR; PG8_SCHED;
	s_setprio 1
	s_waitcnt lgkmcnt(0)
	v_mfma_f32_16x16x32_bf16 v[62:65], v[156:159], v[212:215], 0
	v_mfma_f32_16x16x32_bf16 v[58:61], v[164:167], v[212:215], 0
	v_mfma_f32_16x16x32_bf16 v[46:49], v[156:159], v[220:223], 0
	v_mfma_f32_16x16x32_bf16 v[42:45], v[164:167], v[220:223], 0
	v_mfma_f32_16x16x32_bf16 v[30:33], v[156:159], v[228:231], 0
	v_mfma_f32_16x16x32_bf16 v[26:29], v[164:167], v[228:231], 0
	v_mfma_f32_16x16x32_bf16 v[14:17], v[156:159], v[236:239], 0
	v_mfma_f32_16x16x32_bf16 v[10:13], v[164:167], v[236:239], 0
	v_mfma_f32_16x16x32_bf16 v[62:65], v[160:163], v[216:219], v[62:65]
	v_mfma_f32_16x16x32_bf16 v[58:61], v[168:171], v[216:219], v[58:61]
	v_mfma_f32_16x16x32_bf16 v[46:49], v[160:163], v[224:227], v[46:49]
	v_mfma_f32_16x16x32_bf16 v[42:45], v[168:171], v[224:227], v[42:45]
	v_mfma_f32_16x16x32_bf16 v[30:33], v[160:163], v[232:235], v[30:33]
	v_mfma_f32_16x16x32_bf16 v[26:29], v[168:171], v[232:235], v[26:29]
	v_mfma_f32_16x16x32_bf16 v[14:17], v[160:163], v[240:243], v[14:17]
	v_mfma_f32_16x16x32_bf16 v[10:13], v[168:171], v[240:243], v[10:13]
	s_setprio 0
	s_setprio 1
	v_mfma_f32_16x16x32_bf16 v[54:57], v[172:175], v[212:215], 0
	v_mfma_f32_16x16x32_bf16 v[50:53], v[180:183], v[212:215], 0
	v_mfma_f32_16x16x32_bf16 v[38:41], v[172:175], v[220:223], 0
	v_mfma_f32_16x16x32_bf16 v[34:37], v[180:183], v[220:223], 0
	v_mfma_f32_16x16x32_bf16 v[22:25], v[172:175], v[228:231], 0
	v_mfma_f32_16x16x32_bf16 v[18:21], v[180:183], v[228:231], 0
	v_mfma_f32_16x16x32_bf16 v[6:9], v[172:175], v[236:239], 0
	v_mfma_f32_16x16x32_bf16 v[2:5], v[180:183], v[236:239], 0
	v_mfma_f32_16x16x32_bf16 v[54:57], v[176:179], v[216:219], v[54:57]
	v_mfma_f32_16x16x32_bf16 v[50:53], v[208:211], v[216:219], v[50:53]
	v_mfma_f32_16x16x32_bf16 v[38:41], v[176:179], v[224:227], v[38:41]
	v_mfma_f32_16x16x32_bf16 v[34:37], v[208:211], v[224:227], v[34:37]
	v_mfma_f32_16x16x32_bf16 v[22:25], v[176:179], v[232:235], v[22:25]
	v_mfma_f32_16x16x32_bf16 v[18:21], v[208:211], v[232:235], v[18:21]
	v_mfma_f32_16x16x32_bf16 v[6:9], v[176:179], v[240:243], v[6:9]
	v_mfma_f32_16x16x32_bf16 v[2:5], v[208:211], v[240:243], v[2:5]
	s_setprio 0
	s_barrier
	s_add_i32 s71, 0, 0x18000
	v_add_u32_e32 v155, s71, v145
	s_add_i32 s72, 0, 0x1c000
	ds_read_b128 v[156:159], v155
	ds_read_b128 v[160:163], v155 offset:1024
	ds_read_b128 v[164:167], v155 offset:2048
	ds_read_b128 v[168:171], v155 offset:3072
	v_add_u32_e32 v155, s72, v145
	ds_read_b128 v[172:175], v155
	ds_read_b128 v[176:179], v155 offset:1024
	ds_read_b128 v[180:183], v155 offset:2048
	ds_read_b128 v[208:211], v155 offset:3072
	s_add_u32 s40, s40, 0x40000
	s_addc_u32 s41, s41, 0
	s_mov_b32 m0, s82
	v_lshl_add_u64 v[248:249], s[40:41], 0, v[132:133]
	ds_read_b128 v[212:215], v154 offset:32768
	ds_read_b128 v[216:219], v154 offset:33792
	ds_read_b128 v[220:223], v154 offset:34816
	ds_read_b128 v[224:227], v154 offset:35840
	ds_read_b128 v[228:231], v154 offset:36864
	ds_read_b128 v[232:235], v154 offset:37888
	ds_read_b128 v[236:239], v154 offset:38912
	ds_read_b128 v[240:243], v154 offset:39936
	global_load_lds_dwordx4 v[248:249], off
	v_lshl_add_u64 v[248:249], s[40:41], 0, v[130:131]
	s_mov_b32 m0, s83
	s_nop 0
	global_load_lds_dwordx4 v[248:249], off
	s_waitcnt vmcnt(8)
	s_waitcnt lgkmcnt(0)
	s_barrier
	s_setprio 1
	s_waitcnt lgkmcnt(0)
	v_mfma_f32_16x16x32_bf16 v[126:129], v[156:159], v[212:215], v[126:129]
	v_mfma_f32_16x16x32_bf16 v[122:125], v[164:167], v[212:215], v[122:125]
	v_mfma_f32_16x16x32_bf16 v[110:113], v[156:159], v[220:223], v[110:113]
	v_mfma_f32_16x16x32_bf16 v[106:109], v[164:167], v[220:223], v[106:109]
	v_mfma_f32_16x16x32_bf16 v[94:97], v[156:159], v[228:231], v[94:97]
	v_mfma_f32_16x16x32_bf16 v[90:93], v[164:167], v[228:231], v[90:93]
	v_mfma_f32_16x16x32_bf16 v[78:81], v[156:159], v[236:239], v[78:81]
	v_mfma_f32_16x16x32_bf16 v[74:77], v[164:167], v[236:239], v[74:77]
	v_mfma_f32_16x16x32_bf16 v[126:129], v[160:163], v[216:219], v[126:129]
	v_mfma_f32_16x16x32_bf16 v[122:125], v[168:171], v[216:219], v[122:125]
	v_mfma_f32_16x16x32_bf16 v[110:113], v[160:163], v[224:227], v[110:113]
	v_mfma_f32_16x16x32_bf16 v[106:109], v[168:171], v[224:227], v[106:109]
	v_mfma_f32_16x16x32_bf16 v[94:97], v[160:163], v[232:235], v[94:97]
	v_mfma_f32_16x16x32_bf16 v[90:93], v[168:171], v[232:235], v[90:93]
	v_mfma_f32_16x16x32_bf16 v[78:81], v[160:163], v[240:243], v[78:81]
	v_mfma_f32_16x16x32_bf16 v[74:77], v[168:171], v[240:243], v[74:77]
	s_setprio 0
	s_setprio 1
	v_mfma_f32_16x16x32_bf16 v[118:121], v[172:175], v[212:215], v[118:121]
	v_mfma_f32_16x16x32_bf16 v[114:117], v[180:183], v[212:215], v[114:117]
	v_mfma_f32_16x16x32_bf16 v[102:105], v[172:175], v[220:223], v[102:105]
	v_mfma_f32_16x16x32_bf16 v[98:101], v[180:183], v[220:223], v[98:101]
	v_mfma_f32_16x16x32_bf16 v[86:89], v[172:175], v[228:231], v[86:89]
	v_mfma_f32_16x16x32_bf16 v[82:85], v[180:183], v[228:231], v[82:85]
	v_mfma_f32_16x16x32_bf16 v[70:73], v[172:175], v[236:239], v[70:73]
	v_mfma_f32_16x16x32_bf16 v[66:69], v[180:183], v[236:239], v[66:69]
	v_mfma_f32_16x16x32_bf16 v[118:121], v[176:179], v[216:219], v[118:121]
	v_mfma_f32_16x16x32_bf16 v[114:117], v[208:211], v[216:219], v[114:117]
	v_mfma_f32_16x16x32_bf16 v[102:105], v[176:179], v[224:227], v[102:105]
	v_mfma_f32_16x16x32_bf16 v[98:101], v[208:211], v[224:227], v[98:101]
	v_mfma_f32_16x16x32_bf16 v[86:89], v[176:179], v[232:235], v[86:89]
	v_mfma_f32_16x16x32_bf16 v[82:85], v[208:211], v[232:235], v[82:85]
	v_mfma_f32_16x16x32_bf16 v[70:73], v[176:179], v[240:243], v[70:73]
	v_mfma_f32_16x16x32_bf16 v[66:69], v[208:211], v[240:243], v[66:69]
	s_setprio 0
	s_barrier
; #define PG8_STAGE(bufoff, gbase, voff) do { _Pragma("unroll") for (int _i = 0; _i < 2; ++_i) \
;         __builtin_amdgcn_global_load_lds((const unsigned*)((const char*)(gbase) + (voff)[_i]), (PG8_LAS unsigned*)(lds + (bufoff) + ldsw + _i * 8192), 16, 0, 0); } while (0)
; #define PG8_LDA(dst, b, h) do { _Pragma("unroll") for (int m = 0; m < 4; ++m) _Pragma("unroll") for (int k = 0; k < 2; ++k) dst[m][k] = *(const PG8_LAS bf16x8*)(lds + PG8_SA(b, h) + aoff + m * 2048 + k * 1024); } while (0)
; #define PG8_LDB(dst, b, h) do { _Pragma("unroll") for (int n = 0; n < 2; ++n) _Pragma("unroll") for (int k = 0; k < 2; ++k) dst[n][k] = *(const PG8_LAS bf16x8*)(lds + PG8_SB(b, h) + boff + n * 2048 + k * 1024); } while (0)
; #define PG8_MMA(ai, bj, At, Bt) do { __builtin_amdgcn_s_setprio(1); _Pragma("unroll") for (int m = 0; m < 4; ++m) _Pragma("unroll") for (int n = 0; n < 2; ++n) _Pragma("unroll") for (int k = 0; k < 2; ++k) \
;         acc[ai][bj][m][n] = __builtin_amdgcn_mfma_f32_16x16x32_bf16(Bt[n][k], At[m][k], acc[ai][bj][m][n], 0, 0, 0); __builtin_amdgcn_s_setprio(0); } while (0)
; #define PG8_WAIT_V(n) asm volatile("s_waitcnt vmcnt(" #n ")" ::: "memory")
; #define PG8_WAIT_L(n) asm volatile("s_waitcnt lgkmcnt(" #n ")" ::: "memory")
; #define PG8_BAR __builtin_amdgcn_s_barrier()
; #define PG8_SCHED __builtin_amdgcn_sched_barrier(0)
; template <class Epi, class Sched, bool ALIGN_EPI = false, bool SP2 = false>
; __device__ __forceinline__ void gemm_phase(PG8_LAS unsigned char* lds, const Gemm g, const Sched& S, const Epi& E) {
;     ...
;             PG8_LDB(B0, 0, 0); PG8_LDB(B1, 0, 1); PG8_SCHED; PG8_LDA(At, 0, 0); PG8_STAGE(PG8_SA(1, 1), a1 + hstep, voffA);
;     ...
;             PG8_LDA(At, 1, 1); PG8_STAGE(PG8_SB(1, 0), b3, voffB); PG8_STAGE(PG8_SB(1, 1), b3 + hstep, voffB); PG8_STAGE(PG8_SA(1, 0), a3, voffA);
;             PG8_WAIT_V(8); PG8_WAIT_L(0); PG8_BAR; PG8_MMA(1, 0, At, B0); PG8_MMA(1, 1, At, B1); PG8_BAR; PG8_SCHED;
	s_add_i32 s40, s71, s80
	v_lshl_add_u64 v[202:203], v[202:203], 0, s[66:67]
	s_mov_b32 m0, s40
	ds_read_b128 v[212:215], v154 offset:49152
	ds_read_b128 v[216:219], v154 offset:50176
	ds_read_b128 v[220:223], v154 offset:51200
	ds_read_b128 v[224:227], v154 offset:52224
	ds_read_b128 v[228:231], v154 offset:53248
	ds_read_b128 v[232:235], v154 offset:54272
	ds_read_b128 v[236:239], v154 offset:55296
	ds_read_b128 v[240:243], v154 offset:56320
	global_load_lds_dwordx4 v[202:203], off
	s_add_i32 m0, s40, 0x2000
	s_add_u32 s34, s34, 0x40080
	v_lshl_add_u64 v[202:203], v[204:205], 0, s[66:67]
	s_addc_u32 s35, s35, 0
	s_add_i32 s40, s72, s80
	global_load_lds_dwordx4 v[202:203], off
	v_lshl_add_u64 v[202:203], s[34:35], 0, v[132:133]
	s_mov_b32 m0, s40
	s_nop 0
	global_load_lds_dwordx4 v[202:203], off
	v_lshl_add_u64 v[202:203], s[34:35], 0, v[130:131]
	s_add_i32 m0, s40, 0x2000
	s_nop 0
	global_load_lds_dwordx4 v[202:203], off
	v_lshl_add_u64 v[202:203], v[244:245], 0, s[66:67]
	s_mov_b32 m0, s84
	s_nop 0
	global_load_lds_dwordx4 v[202:203], off
	v_lshl_add_u64 v[202:203], v[246:247], 0, s[66:67]
	s_mov_b32 m0, s85
	s_nop 0
	global_load_lds_dwordx4 v[202:203], off
	s_waitcnt vmcnt(8)
	s_waitcnt lgkmcnt(0)
	s_barrier
	s_setprio 1
	s_waitcnt lgkmcnt(0)
	v_mfma_f32_16x16x32_bf16 v[62:65], v[156:159], v[212:215], v[62:65]
	v_mfma_f32_16x16x32_bf16 v[58:61], v[164:167], v[212:215], v[58:61]
	v_mfma_f32_16x16x32_bf16 v[46:49], v[156:159], v[220:223], v[46:49]
	v_mfma_f32_16x16x32_bf16 v[42:45], v[164:167], v[220:223], v[42:45]
	v_mfma_f32_16x16x32_bf16 v[30:33], v[156:159], v[228:231], v[30:33]
	v_mfma_f32_16x16x32_bf16 v[26:29], v[164:167], v[228:231], v[26:29]
	v_mfma_f32_16x16x32_bf16 v[14:17], v[156:159], v[236:239], v[14:17]
	v_mfma_f32_16x16x32_bf16 v[10:13], v[164:167], v[236:239], v[10:13]
	v_mfma_f32_16x16x32_bf16 v[62:65], v[160:163], v[216:219], v[62:65]
	v_mfma_f32_16x16x32_bf16 v[58:61], v[168:171], v[216:219], v[58:61]
	v_mfma_f32_16x16x32_bf16 v[46:49], v[160:163], v[224:227], v[46:49]
	v_mfma_f32_16x16x32_bf16 v[42:45], v[168:171], v[224:227], v[42:45]
	v_mfma_f32_16x16x32_bf16 v[30:33], v[160:163], v[232:235], v[30:33]
	v_mfma_f32_16x16x32_bf16 v[26:29], v[168:171], v[232:235], v[26:29]
	v_mfma_f32_16x16x32_bf16 v[14:17], v[160:163], v[240:243], v[14:17]
	v_mfma_f32_16x16x32_bf16 v[10:13], v[168:171], v[240:243], v[10:13]
	s_setprio 0
	s_setprio 1
	v_mfma_f32_16x16x32_bf16 v[54:57], v[172:175], v[212:215], v[54:57]
	v_mfma_f32_16x16x32_bf16 v[50:53], v[180:183], v[212:215], v[50:53]
	v_mfma_f32_16x16x32_bf16 v[38:41], v[172:175], v[220:223], v[38:41]
	v_mfma_f32_16x16x32_bf16 v[34:37], v[180:183], v[220:223], v[34:37]
	v_mfma_f32_16x16x32_bf16 v[22:25], v[172:175], v[228:231], v[22:25]
	v_mfma_f32_16x16x32_bf16 v[18:21], v[180:183], v[228:231], v[18:21]
	v_mfma_f32_16x16x32_bf16 v[6:9], v[172:175], v[236:239], v[6:9]
	v_mfma_f32_16x16x32_bf16 v[2:5], v[180:183], v[236:239], v[2:5]
	v_mfma_f32_16x16x32_bf16 v[54:57], v[176:179], v[216:219], v[54:57]
	v_mfma_f32_16x16x32_bf16 v[50:53], v[208:211], v[216:219], v[50:53]
	v_mfma_f32_16x16x32_bf16 v[38:41], v[176:179], v[224:227], v[38:41]
	v_mfma_f32_16x16x32_bf16 v[34:37], v[208:211], v[224:227], v[34:37]
	v_mfma_f32_16x16x32_bf16 v[22:25], v[176:179], v[232:235], v[22:25]
	v_mfma_f32_16x16x32_bf16 v[18:21], v[208:211], v[232:235], v[18:21]
	v_mfma_f32_16x16x32_bf16 v[6:9], v[176:179], v[240:243], v[6:9]
	v_mfma_f32_16x16x32_bf16 v[2:5], v[208:211], v[240:243], v[2:5]
	s_setprio 0
	s_barrier
	s_add_i32 s62, s62, 2
	s_add_u32 s30, s30, 0x100
	s_addc_u32 s31, s31, 0
	s_add_u32 s52, s52, 0x100
	s_addc_u32 s54, s54, 0
	s_cmp_gt_u32 s62, 13
	s_cbranch_scc0 .LBB0_163
	s_branch .Lku_exit
	s_nop 0
	s_nop 0
	s_nop 0
	s_nop 0
	s_nop 0
	s_nop 0
	s_nop 0
	s_nop 0
	s_nop 0
	s_nop 0
	s_nop 0
.LBB0_163:
	s_add_u32 s34, s30, 0xfffc0080
	s_addc_u32 s35, s31, -1
	s_add_i32 s71, 0, 0x10000
	s_cmp_eq_u32 s62, 12
	s_cselect_b32 s41, s21, s35
	s_cselect_b32 s40, s27, s34
	v_add_u32_e32 v155, s71, v145
	s_cselect_b32 s35, s19, s54
	s_cselect_b32 s34, s50, s52
	s_add_i32 s74, 0, 0x14000
	ds_read_b128 v[156:159], v155
	ds_read_b128 v[160:163], v155 offset:1024
	ds_read_b128 v[164:167], v155 offset:2048
	ds_read_b128 v[168:171], v155 offset:3072
	v_add_u32_e32 v155, s74, v145
	ds_read_b128 v[172:175], v155
	ds_read_b128 v[176:179], v155 offset:1024
	ds_read_b128 v[180:183], v155 offset:2048
	ds_read_b128 v[208:211], v155 offset:3072
	v_lshl_add_u64 v[202:203], s[30:31], 0, v[134:135]
	s_add_i32 m0, s29, 0xc000
	ds_read_b128 v[212:215], v154
	ds_read_b128 v[216:219], v154 offset:1024
	ds_read_b128 v[220:223], v154 offset:2048
	ds_read_b128 v[224:227], v154 offset:3072
	ds_read_b128 v[228:231], v154 offset:4096
	ds_read_b128 v[232:235], v154 offset:5120
	ds_read_b128 v[236:239], v154 offset:6144
	ds_read_b128 v[240:243], v154 offset:7168
	global_load_lds_dwordx4 v[202:203], off
	v_lshl_add_u64 v[202:203], s[30:31], 0, v[136:137]
	s_add_i32 m0, s29, 0xe000
	s_nop 0
	global_load_lds_dwordx4 v[202:203], off
	s_waitcnt vmcnt(8)
	s_waitcnt lgkmcnt(0)
	s_barrier
; #define PG8_STAGE(bufoff, gbase, voff) do { _Pragma("unroll") for (int _i = 0; _i < 2; ++_i) \
;         __builtin_amdgcn_global_load_lds((const unsigned*)((const char*)(gbase) + (voff)[_i]), (PG8_LAS unsigned*)(lds + (bufoff) + ldsw + _i * 8192), 16, 0, 0); } while (0)
; #define PG8_LDA(dst, b, h) do { _Pragma("unroll") for (int m = 0; m < 4; ++m) _Pragma("unroll") for (int k = 0; k < 2; ++k) dst[m][k] = *(const PG8_LAS bf16x8*)(lds + PG8_SA(b, h) + aoff + m * 2048 + k * 1024); } while (0)
; #define PG8_LDB(dst, b, h) do { _Pragma("unroll") for (int n = 0; n < 2; ++n) _Pragma("unroll") for (int k = 0; k < 2; ++k) dst[n][k] = *(const PG8_LAS bf16x8*)(lds + PG8_SB(b, h) + boff + n * 2048 + k * 1024); } while (0)
; #define PG8_MMA(ai, bj, At, Bt) do { __builtin_amdgcn_s_setprio(1); _Pragma("unroll") for (int m = 0; m < 4; ++m) _Pragma("unroll") for (int n = 0; n < 2; ++n) _Pragma("unroll") for (int k = 0; k < 2; ++k) \
;         acc[ai][bj][m][n] = __builtin_amdgcn_mfma_f32_16x16x32_bf16(Bt[n][k], At[m][k], acc[ai][bj][m][n], 0, 0, 0); __builtin_amdgcn_s_setprio(0); } while (0)
; #define PG8_WAIT_V(n) asm volatile("s_waitcnt vmcnt(" #n ")" ::: "memory")
; #define PG8_WAIT_L(n) asm volatile("s_waitcnt lgkmcnt(" #n ")" ::: "memory")
; #define PG8_BAR __builtin_amdgcn_s_barrier()
; #define PG8_SCHED __builtin_amdgcn_sched_barrier(0)
; template <class Epi, class Sched, bool ALIGN_EPI = false, bool SP2 = false>
; __device__ __forceinline__ void gemm_phase(PG8_LAS unsigned char* lds, const Gemm g, const Sched& S, const Epi& E) {
;     ...
;             PG8_WAIT_V(8); PG8_WAIT_L(0); PG8_BAR; PG8_MMA(0, 0, At, B0); PG8_MMA(0, 1, At, B1); PG8_BAR; PG8_SCHED;
;             PG8_LDA(At, 0, 1); PG8_STAGE(PG8_SB(0, 0), b2, voffB); PG8_STAGE(PG8_SB(0, 1), b2 + hstep, voffB); PG8_STAGE(PG8_SA(0, 0), a2, voffA);
;             PG8_WAIT_V(8); PG8_WAIT_L(0); PG8_BAR; PG8_MMA(1, 0, At, B0); PG8_MMA(1, 1, At, B1); PG8_BAR; PG8_SCHED;
;             PG8_LDB(B0, 1, 0); PG8_LDB(B1, 1, 1); PG8_SCHED; PG8_LDA(At, 1, 0); PG8_STAGE(PG8_SA(0, 1), a2 + hstep, voffA);
	s_setprio 1
	s_waitcnt lgkmcnt(0)
	v_mfma_f32_16x16x32_bf16 v[126:129], v[156:159], v[212:215], v[126:129]
	v_mfma_f32_16x16x32_bf16 v[122:125], v[164:167], v[212:215], v[122:125]
	v_mfma_f32_16x16x32_bf16 v[110:113], v[156:159], v[220:223], v[110:113]
	v_mfma_f32_16x16x32_bf16 v[106:109], v[164:167], v[220:223], v[106:109]
	v_mfma_f32_16x16x32_bf16 v[94:97], v[156:159], v[228:231], v[94:97]
	v_mfma_f32_16x16x32_bf16 v[90:93], v[164:167], v[228:231], v[90:93]
	v_mfma_f32_16x16x32_bf16 v[78:81], v[156:159], v[236:239], v[78:81]
	v_mfma_f32_16x16x32_bf16 v[74:77], v[164:167], v[236:239], v[74:77]
	v_mfma_f32_16x16x32_bf16 v[126:129], v[160:163], v[216:219], v[126:129]
	v_mfma_f32_16x16x32_bf16 v[122:125], v[168:171], v[216:219], v[122:125]
	v_mfma_f32_16x16x32_bf16 v[110:113], v[160:163], v[224:227], v[110:113]
	v_mfma_f32_16x16x32_bf16 v[106:109], v[168:171], v[224:227], v[106:109]
	v_mfma_f32_16x16x32_bf16 v[94:97], v[160:163], v[232:235], v[94:97]
	v_mfma_f32_16x16x32_bf16 v[90:93], v[168:171], v[232:235], v[90:93]
	v_mfma_f32_16x16x32_bf16 v[78:81], v[160:163], v[240:243], v[78:81]
	v_mfma_f32_16x16x32_bf16 v[74:77], v[168:171], v[240:243], v[74:77]
	s_setprio 0
	s_setprio 1
	v_mfma_f32_16x16x32_bf16 v[118:121], v[172:175], v[212:215], v[118:121]
	v_mfma_f32_16x16x32_bf16 v[114:117], v[180:183], v[212:215], v[114:117]
	v_mfma_f32_16x16x32_bf16 v[102:105], v[172:175], v[220:223], v[102:105]
	v_mfma_f32_16x16x32_bf16 v[98:101], v[180:183], v[220:223], v[98:101]
	v_mfma_f32_16x16x32_bf16 v[86:89], v[172:175], v[228:231], v[86:89]
	v_mfma_f32_16x16x32_bf16 v[82:85], v[180:183], v[228:231], v[82:85]
	v_mfma_f32_16x16x32_bf16 v[70:73], v[172:175], v[236:239], v[70:73]
	v_mfma_f32_16x16x32_bf16 v[66:69], v[180:183], v[236:239], v[66:69]
	v_mfma_f32_16x16x32_bf16 v[118:121], v[176:179], v[216:219], v[118:121]
	v_mfma_f32_16x16x32_bf16 v[114:117], v[208:211], v[216:219], v[114:117]
	v_mfma_f32_16x16x32_bf16 v[102:105], v[176:179], v[224:227], v[102:105]
	v_mfma_f32_16x16x32_bf16 v[98:101], v[208:211], v[224:227], v[98:101]
	v_mfma_f32_16x16x32_bf16 v[86:89], v[176:179], v[232:235], v[86:89]
	v_mfma_f32_16x16x32_bf16 v[82:85], v[208:211], v[232:235], v[82:85]
	v_mfma_f32_16x16x32_bf16 v[70:73], v[176:179], v[240:243], v[70:73]
	v_mfma_f32_16x16x32_bf16 v[66:69], v[208:211], v[240:243], v[66:69]
	s_setprio 0
	s_barrier
	s_add_i32 s71, s71, s80
	v_lshl_add_u64 v[202:203], s[34:35], 0, v[132:133]
	s_mov_b32 m0, s71
	ds_read_b128 v[212:215], v154 offset:16384
	ds_read_b128 v[216:219], v154 offset:17408
	ds_read_b128 v[220:223], v154 offset:18432
	ds_read_b128 v[224:227], v154 offset:19456
	ds_read_b128 v[228:231], v154 offset:20480
	ds_read_b128 v[232:235], v154 offset:21504
	ds_read_b128 v[236:239], v154 offset:22528
	ds_read_b128 v[240:243], v154 offset:23552
	global_load_lds_dwordx4 v[202:203], off
	s_add_i32 m0, s71, 0x2000
	s_add_u32 s72, s34, 0x40000
	v_lshl_add_u64 v[204:205], s[34:35], 0, v[130:131]
	s_addc_u32 s73, s35, 0
	s_add_i32 s71, s74, s80
	global_load_lds_dwordx4 v[204:205], off
	v_lshl_add_u64 v[244:245], s[72:73], 0, v[132:133]
	s_mov_b32 m0, s71
	v_lshl_add_u64 v[246:247], s[40:41], 0, v[130:131]
	global_load_lds_dwordx4 v[244:245], off
	v_lshl_add_u64 v[244:245], s[72:73], 0, v[130:131]
	s_add_i32 m0, s71, 0x2000
	s_nop 0
	global_load_lds_dwordx4 v[244:245], off
	v_lshl_add_u64 v[244:245], s[40:41], 0, v[132:133]
	s_mov_b32 m0, s29
	s_nop 0
	global_load_lds_dwordx4 v[244:245], off
	s_mov_b32 m0, s81
	s_nop 0
	global_load_lds_dwordx4 v[246:247], off
	s_waitcnt vmcnt(8)
	s_waitcnt lgkmcnt(0)
	s_barrier
	s_setprio 1
	s_waitcnt lgkmcnt(0)
	v_mfma_f32_16x16x32_bf16 v[62:65], v[156:159], v[212:215], v[62:65]
	v_mfma_f32_16x16x32_bf16 v[58:61], v[164:167], v[212:215], v[58:61]
	v_mfma_f32_16x16x32_bf16 v[46:49], v[156:159], v[220:223], v[46:49]
	v_mfma_f32_16x16x32_bf16 v[42:45], v[164:167], v[220:223], v[42:45]
	v_mfma_f32_16x16x32_bf16 v[30:33], v[156:159], v[228:231], v[30:33]
	v_mfma_f32_16x16x32_bf16 v[26:29], v[164:167], v[228:231], v[26:29]
	v_mfma_f32_16x16x32_bf16 v[14:17], v[156:159], v[236:239], v[14:17]
	v_mfma_f32_16x16x32_bf16 v[10:13], v[164:167], v[236:239], v[10:13]
	v_mfma_f32_16x16x32_bf16 v[62:65], v[160:163], v[216:219], v[62:65]
	v_mfma_f32_16x16x32_bf16 v[58:61], v[168:171], v[216:219], v[58:61]
	v_mfma_f32_16x16x32_bf16 v[46:49], v[160:163], v[224:227], v[46:49]
	v_mfma_f32_16x16x32_bf16 v[42:45], v[168:171], v[224:227], v[42:45]
	v_mfma_f32_16x16x32_bf16 v[30:33], v[160:163], v[232:235], v[30:33]
	v_mfma_f32_16x16x32_bf16 v[26:29], v[168:171], v[232:235], v[26:29]
	v_mfma_f32_16x16x32_bf16 v[14:17], v[160:163], v[240:243], v[14:17]
	v_mfma_f32_16x16x32_bf16 v[10:13], v[168:171], v[240:243], v[10:13]
	s_setprio 0
	s_setprio 1
	v_mfma_f32_16x16x32_bf16 v[54:57], v[172:175], v[212:215], v[54:57]
	v_mfma_f32_16x16x32_bf16 v[50:53], v[180:183], v[212:215], v[50:53]
	v_mfma_f32_16x16x32_bf16 v[38:41], v[172:175], v[220:223], v[38:41]
	v_mfma_f32_16x16x32_bf16 v[34:37], v[180:183], v[220:223], v[34:37]
	v_mfma_f32_16x16x32_bf16 v[22:25], v[172:175], v[228:231], v[22:25]
	v_mfma_f32_16x16x32_bf16 v[18:21], v[180:183], v[228:231], v[18:21]
	v_mfma_f32_16x16x32_bf16 v[6:9], v[172:175], v[236:239], v[6:9]
	v_mfma_f32_16x16x32_bf16 v[2:5], v[180:183], v[236:239], v[2:5]
	v_mfma_f32_16x16x32_bf16 v[54:57], v[176:179], v[216:219], v[54:57]
	v_mfma_f32_16x16x32_bf16 v[50:53], v[208:211], v[216:219], v[50:53]
	v_mfma_f32_16x16x32_bf16 v[38:41], v[176:179], v[224:227], v[38:41]
	v_mfma_f32_16x16x32_bf16 v[34:37], v[208:211], v[224:227], v[34:37]
	v_mfma_f32_16x16x32_bf16 v[22:25], v[176:179], v[232:235], v[22:25]
	v_mfma_f32_16x16x32_bf16 v[18:21], v[208:211], v[232:235], v[18:21]
	v_mfma_f32_16x16x32_bf16 v[6:9], v[176:179], v[240:243], v[6:9]
	v_mfma_f32_16x16x32_bf16 v[2:5], v[208:211], v[240:243], v[2:5]
	s_setprio 0
	s_barrier
; #define PG8_STAGE(bufoff, gbase, voff) do { _Pragma("unroll") for (int _i = 0; _i < 2; ++_i) \
;         __builtin_amdgcn_global_load_lds((const unsigned*)((const char*)(gbase) + (voff)[_i]), (PG8_LAS unsigned*)(lds + (bufoff) + ldsw + _i * 8192), 16, 0, 0); } while (0)
; #define PG8_LDA(dst, b, h) do { _Pragma("unroll") for (int m = 0; m < 4; ++m) _Pragma("unroll") for (int k = 0; k < 2; ++k) dst[m][k] = *(const PG8_LAS bf16x8*)(lds + PG8_SA(b, h) + aoff + m * 2048 + k * 1024); } while (0)
; #define PG8_LDB(dst, b, h) do { _Pragma("unroll") for (int n = 0; n < 2; ++n) _Pragma("unroll") for (int k = 0; k < 2; ++k) dst[n][k] = *(const PG8_LAS bf16x8*)(lds + PG8_SB(b, h) + boff + n * 2048 + k * 1024); } while (0)
; #define PG8_MMA(ai, bj, At, Bt) do { __builtin_amdgcn_s_setprio(1); _Pragma("unroll") for (int m = 0; m < 4; ++m) _Pragma("unroll") for (int n = 0; n < 2; ++n) _Pragma("unroll") for (int k = 0; k < 2; ++k) \
;         acc[ai][bj][m][n] = __builtin_amdgcn_mfma_f32_16x16x32_bf16(Bt[n][k], At[m][k], acc[ai][bj][m][n], 0, 0, 0); __builtin_amdgcn_s_setprio(0); } while (0)
; #define PG8_WAIT_V(n) asm volatile("s_waitcnt vmcnt(" #n ")" ::: "memory")
; #define PG8_WAIT_L(n) asm volatile("s_waitcnt lgkmcnt(" #n ")" ::: "memory")
; #define PG8_BAR __builtin_amdgcn_s_barrier()
; #define PG8_SCHED __builtin_amdgcn_sched_barrier(0)
; template <class Epi, class Sched, bool ALIGN_EPI = false, bool SP2 = false>
; __device__ __forceinline__ void gemm_phase(PG8_LAS unsigned char* lds, const Gemm g, const Sched& S, const Epi& E) {
;     ...
;             PG8_LDB(B0, 1, 0); PG8_LDB(B1, 1, 1); PG8_SCHED; PG8_LDA(At, 1, 0); PG8_STAGE(PG8_SA(0, 1), a2 + hstep, voffA);
;             PG8_WAIT_V(8); PG8_WAIT_L(0); PG8_BAR; PG8_MMA(0, 0, At, B0); PG8_MMA(0, 1, At, B1); PG8_BAR; PG8_SCHED;
	s_add_i32 s71, 0, 0x18000
	v_add_u32_e32 v155, s71, v145
	s_add_i32 s72, 0, 0x1c000
	ds_read_b128 v[156:159], v155
	ds_read_b128 v[160:163], v155 offset:1024
	ds_read_b128 v[164:167], v155 offset:2048
	ds_read_b128 v[168:171], v155 offset:3072
	v_add_u32_e32 v155, s72, v145
	ds_read_b128 v[172:175], v155
	ds_read_b128 v[176:179], v155 offset:1024
	ds_read_b128 v[180:183], v155 offset:2048
	ds_read_b128 v[208:211], v155 offset:3072
	s_add_u32 s40, s40, 0x40000
	s_addc_u32 s41, s41, 0
	s_mov_b32 m0, s82
	v_lshl_add_u64 v[248:249], s[40:41], 0, v[132:133]
	ds_read_b128 v[212:215], v154 offset:32768
	ds_read_b128 v[216:219], v154 offset:33792
	ds_read_b128 v[220:223], v154 offset:34816
	ds_read_b128 v[224:227], v154 offset:35840
	ds_read_b128 v[228:231], v154 offset:36864
	ds_read_b128 v[232:235], v154 offset:37888
	ds_read_b128 v[236:239], v154 offset:38912
	ds_read_b128 v[240:243], v154 offset:39936
	global_load_lds_dwordx4 v[248:249], off
	v_lshl_add_u64 v[248:249], s[40:41], 0, v[130:131]
	s_mov_b32 m0, s83
	s_nop 0
	global_load_lds_dwordx4 v[248:249], off
	s_waitcnt vmcnt(8)
	s_waitcnt lgkmcnt(0)
	s_barrier
	s_setprio 1
	s_waitcnt lgkmcnt(0)
	v_mfma_f32_16x16x32_bf16 v[126:129], v[156:159], v[212:215], v[126:129]
	v_mfma_f32_16x16x32_bf16 v[122:125], v[164:167], v[212:215], v[122:125]
	v_mfma_f32_16x16x32_bf16 v[110:113], v[156:159], v[220:223], v[110:113]
	v_mfma_f32_16x16x32_bf16 v[106:109], v[164:167], v[220:223], v[106:109]
	v_mfma_f32_16x16x32_bf16 v[94:97], v[156:159], v[228:231], v[94:97]
	v_mfma_f32_16x16x32_bf16 v[90:93], v[164:167], v[228:231], v[90:93]
	v_mfma_f32_16x16x32_bf16 v[78:81], v[156:159], v[236:239], v[78:81]
	v_mfma_f32_16x16x32_bf16 v[74:77], v[164:167], v[236:239], v[74:77]
	v_mfma_f32_16x16x32_bf16 v[126:129], v[160:163], v[216:219], v[126:129]
	v_mfma_f32_16x16x32_bf16 v[122:125], v[168:171], v[216:219], v[122:125]
	v_mfma_f32_16x16x32_bf16 v[110:113], v[160:163], v[224:227], v[110:113]
	v_mfma_f32_16x16x32_bf16 v[106:109], v[168:171], v[224:227], v[106:109]
	v_mfma_f32_16x16x32_bf16 v[94:97], v[160:163], v[232:235], v[94:97]
	v_mfma_f32_16x16x32_bf16 v[90:93], v[168:171], v[232:235], v[90:93]
	v_mfma_f32_16x16x32_bf16 v[78:81], v[160:163], v[240:243], v[78:81]
	v_mfma_f32_16x16x32_bf16 v[74:77], v[168:171], v[240:243], v[74:77]
	s_setprio 0
	s_setprio 1
	v_mfma_f32_16x16x32_bf16 v[118:121], v[172:175], v[212:215], v[118:121]
	v_mfma_f32_16x16x32_bf16 v[114:117], v[180:183], v[212:215], v[114:117]
	v_mfma_f32_16x16x32_bf16 v[102:105], v[172:175], v[220:223], v[102:105]
	v_mfma_f32_16x16x32_bf16 v[98:101], v[180:183], v[220:223], v[98:101]
	v_mfma_f32_16x16x32_bf16 v[86:89], v[172:175], v[228:231], v[86:89]
	v_mfma_f32_16x16x32_bf16 v[82:85], v[180:183], v[228:231], v[82:85]
	v_mfma_f32_16x16x32_bf16 v[70:73], v[172:175], v[236:239], v[70:73]
	v_mfma_f32_16x16x32_bf16 v[66:69], v[180:183], v[236:239], v[66:69]
	v_mfma_f32_16x16x32_bf16 v[118:121], v[176:179], v[216:219], v[118:121]
	v_mfma_f32_16x16x32_bf16 v[114:117], v[208:211], v[216:219], v[114:117]
	v_mfma_f32_16x16x32_bf16 v[102:105], v[176:179], v[224:227], v[102:105]
	v_mfma_f32_16x16x32_bf16 v[98:101], v[208:211], v[224:227], v[98:101]
	v_mfma_f32_16x16x32_bf16 v[86:89], v[176:179], v[232:235], v[86:89]
	v_mfma_f32_16x16x32_bf16 v[82:85], v[208:211], v[232:235], v[82:85]
	v_mfma_f32_16x16x32_bf16 v[70:73], v[176:179], v[240:243], v[70:73]
	v_mfma_f32_16x16x32_bf16 v[66:69], v[208:211], v[240:243], v[66:69]
	s_setprio 0
	s_barrier
; #define PG8_STAGE(bufoff, gbase, voff) do { _Pragma("unroll") for (int _i = 0; _i < 2; ++_i) \
;         __builtin_amdgcn_global_load_lds((const unsigned*)((const char*)(gbase) + (voff)[_i]), (PG8_LAS unsigned*)(lds + (bufoff) + ldsw + _i * 8192), 16, 0, 0); } while (0)
; #define PG8_LDA(dst, b, h) do { _Pragma("unroll") for (int m = 0; m < 4; ++m) _Pragma("unroll") for (int k = 0; k < 2; ++k) dst[m][k] = *(const PG8_LAS bf16x8*)(lds + PG8_SA(b, h) + aoff + m * 2048 + k * 1024); } while (0)
; #define PG8_MMA(ai, bj, At, Bt) do { __builtin_amdgcn_s_setprio(1); _Pragma("unroll") for (int m = 0; m < 4; ++m) _Pragma("unroll") for (int n = 0; n < 2; ++n) _Pragma("unroll") for (int k = 0; k < 2; ++k) \
;         acc[ai][bj][m][n] = __builtin_amdgcn_mfma_f32_16x16x32_bf16(Bt[n][k], At[m][k], acc[ai][bj][m][n], 0, 0, 0); __builtin_amdgcn_s_setprio(0); } while (0)
; #define PG8_WAIT_V(n) asm volatile("s_waitcnt vmcnt(" #n ")" ::: "memory")
; #define PG8_WAIT_L(n) asm volatile("s_waitcnt lgkmcnt(" #n ")" ::: "memory")
; #define PG8_BAR __builtin_amdgcn_s_barrier()
; #define PG8_SCHED __builtin_amdgcn_sched_barrier(0)
; template <class Epi, class Sched, bool ALIGN_EPI = false, bool SP2 = false>
; __device__ __forceinline__ void gemm_phase(PG8_LAS unsigned char* lds, const Gemm g, const Sched& S, const Epi& E) {
;     ...
;         for (int t = 0; t < nt; t += 2) {
;     ...
;             PG8_LDA(At, 1, 1); PG8_STAGE(PG8_SB(1, 0), b3, voffB); PG8_STAGE(PG8_SB(1, 1), b3 + hstep, voffB); PG8_STAGE(PG8_SA(1, 0), a3, voffA);
;             PG8_WAIT_V(8); PG8_WAIT_L(0); PG8_BAR; PG8_MMA(1, 0, At, B0); PG8_MMA(1, 1, At, B1); PG8_BAR; PG8_SCHED;
	s_add_i32 s40, s71, s80
	v_lshl_add_u64 v[202:203], v[202:203], 0, s[66:67]
	s_mov_b32 m0, s40
	ds_read_b128 v[212:215], v154 offset:49152
	ds_read_b128 v[216:219], v154 offset:50176
	ds_read_b128 v[220:223], v154 offset:51200
	ds_read_b128 v[224:227], v154 offset:52224
	ds_read_b128 v[228:231], v154 offset:53248
	ds_read_b128 v[232:235], v154 offset:54272
	ds_read_b128 v[236:239], v154 offset:55296
	ds_read_b128 v[240:243], v154 offset:56320
	global_load_lds_dwordx4 v[202:203], off
	s_add_i32 m0, s40, 0x2000
	s_add_u32 s34, s34, 0x40080
	v_lshl_add_u64 v[202:203], v[204:205], 0, s[66:67]
	s_addc_u32 s35, s35, 0
	s_add_i32 s40, s72, s80
	global_load_lds_dwordx4 v[202:203], off
	v_lshl_add_u64 v[202:203], s[34:35], 0, v[132:133]
	s_mov_b32 m0, s40
	s_nop 0
	global_load_lds_dwordx4 v[202:203], off
	v_lshl_add_u64 v[202:203], s[34:35], 0, v[130:131]
	s_add_i32 m0, s40, 0x2000
	s_nop 0
	global_load_lds_dwordx4 v[202:203], off
	v_lshl_add_u64 v[202:203], v[244:245], 0, s[66:67]
	s_mov_b32 m0, s84
	s_nop 0
	global_load_lds_dwordx4 v[202:203], off
	v_lshl_add_u64 v[202:203], v[246:247], 0, s[66:67]
	s_mov_b32 m0, s85
	s_nop 0
	global_load_lds_dwordx4 v[202:203], off
	s_waitcnt vmcnt(8)
	s_waitcnt lgkmcnt(0)
	s_barrier
	s_setprio 1
	s_waitcnt lgkmcnt(0)
	v_mfma_f32_16x16x32_bf16 v[62:65], v[156:159], v[212:215], v[62:65]
	v_mfma_f32_16x16x32_bf16 v[58:61], v[164:167], v[212:215], v[58:61]
	v_mfma_f32_16x16x32_bf16 v[46:49], v[156:159], v[220:223], v[46:49]
	v_mfma_f32_16x16x32_bf16 v[42:45], v[164:167], v[220:223], v[42:45]
	v_mfma_f32_16x16x32_bf16 v[30:33], v[156:159], v[228:231], v[30:33]
	v_mfma_f32_16x16x32_bf16 v[26:29], v[164:167], v[228:231], v[26:29]
	v_mfma_f32_16x16x32_bf16 v[14:17], v[156:159], v[236:239], v[14:17]
	v_mfma_f32_16x16x32_bf16 v[10:13], v[164:167], v[236:239], v[10:13]
	v_mfma_f32_16x16x32_bf16 v[62:65], v[160:163], v[216:219], v[62:65]
	v_mfma_f32_16x16x32_bf16 v[58:61], v[168:171], v[216:219], v[58:61]
	v_mfma_f32_16x16x32_bf16 v[46:49], v[160:163], v[224:227], v[46:49]
	v_mfma_f32_16x16x32_bf16 v[42:45], v[168:171], v[224:227], v[42:45]
	v_mfma_f32_16x16x32_bf16 v[30:33], v[160:163], v[232:235], v[30:33]
	v_mfma_f32_16x16x32_bf16 v[26:29], v[168:171], v[232:235], v[26:29]
	v_mfma_f32_16x16x32_bf16 v[14:17], v[160:163], v[240:243], v[14:17]
	v_mfma_f32_16x16x32_bf16 v[10:13], v[168:171], v[240:243], v[10:13]
	s_setprio 0
	s_setprio 1
	v_mfma_f32_16x16x32_bf16 v[54:57], v[172:175], v[212:215], v[54:57]
	v_mfma_f32_16x16x32_bf16 v[50:53], v[180:183], v[212:215], v[50:53]
	v_mfma_f32_16x16x32_bf16 v[38:41], v[172:175], v[220:223], v[38:41]
	v_mfma_f32_16x16x32_bf16 v[34:37], v[180:183], v[220:223], v[34:37]
	v_mfma_f32_16x16x32_bf16 v[22:25], v[172:175], v[228:231], v[22:25]
	v_mfma_f32_16x16x32_bf16 v[18:21], v[180:183], v[228:231], v[18:21]
	v_mfma_f32_16x16x32_bf16 v[6:9], v[172:175], v[236:239], v[6:9]
	v_mfma_f32_16x16x32_bf16 v[2:5], v[180:183], v[236:239], v[2:5]
	v_mfma_f32_16x16x32_bf16 v[54:57], v[176:179], v[216:219], v[54:57]
	v_mfma_f32_16x16x32_bf16 v[50:53], v[208:211], v[216:219], v[50:53]
	v_mfma_f32_16x16x32_bf16 v[38:41], v[176:179], v[224:227], v[38:41]
	v_mfma_f32_16x16x32_bf16 v[34:37], v[208:211], v[224:227], v[34:37]
	v_mfma_f32_16x16x32_bf16 v[22:25], v[176:179], v[232:235], v[22:25]
	v_mfma_f32_16x16x32_bf16 v[18:21], v[208:211], v[232:235], v[18:21]
	v_mfma_f32_16x16x32_bf16 v[6:9], v[176:179], v[240:243], v[6:9]
	v_mfma_f32_16x16x32_bf16 v[2:5], v[208:211], v[240:243], v[2:5]
	s_setprio 0
	s_barrier
	s_add_i32 s62, s62, 2
	s_add_u32 s30, s30, 0x100
	s_addc_u32 s31, s31, 0
	s_add_u32 s52, s52, 0x100
	s_addc_u32 s54, s54, 0
	s_cmp_gt_u32 s62, 13
	s_cbranch_scc0 .LBB0_163
	s_branch .Lku_exit
	s_nop 0
	s_nop 0
	s_nop 0
	s_nop 0
	s_nop 0
	s_nop 0
	s_nop 0
	s_nop 0
	s_nop 0
	s_nop 0
	s_nop 0
	s_nop 0
	s_nop 0
	s_nop 0

; __device__ __forceinline__ void na_task(const P& p, int task, int lane, float* ldsw  ) {
;     const int fr = lane & 15, g = lane >> 4;
;     const bf16_t* QK = (const bf16_t*)(p.ws + WS_NAQK); const bf16_t* VT = (const bf16_t*)(p.ws + WS_NAVT); bf16_t* Y = (bf16_t*)(p.ws + WS_A);
;     if (task < 2048) {
;         const int h = task & 7, r = (task >> 3) & 31, b = task >> 8;
;         for (int i = lane; i < 465; i += 64) ldsw[i] = p.rpb[h * 465 + i];
;         AttnState st[4];
;         bf16_t* qlds = (bf16_t*)(ldsw + 512) + fr * 72 + g * 8;
;         const size_t qrow0 = (size_t)b * TLAT + r * 64 + fr;
; #pragma unroll
;         for (int j = 0; j < 4; ++j) {
;             st[j].m = -1e30f; st[j].l = 0.f;
; #pragma unroll
;             for (int dt = 0; dt < 4; ++dt) st[j].o[dt] = (f32x4){0.f, 0.f, 0.f, 0.f};
;             const bf16_t* qp = QK + (qrow0 + j * 16) * 1024 + h * 64 + g * 8;
;             *(bf16x8*)(qlds + j * 16 * 72) = *(const bf16x8*)qp; *(bf16x8*)(qlds + j * 16 * 72 + 32) = *(const bf16x8*)(qp + 32);
;         }
;         const int r0 = clampi(r - 4, 0, 24);
;         const bf16_t* vb = VT + ((size_t)b * 512 + h * 64) * TT;
;         const bf16_t* kbase = QK + 512 + h * 64 + g * 8;
;     ...
;                 if (i < 16) {
;                     const int qcol = j * 16 + fr, cst = clampi(qcol - 8, 0, 48);
; #pragma unroll
;                     for (int q8 = 0; q8 < 8; ++q8) { const int kk = (q8 < 4) ? 4 * g + q8 : 12 + 4 * g + q8; const int kcc = half * 32 + kk;
;                         const bool ok = (kcc >= cst) && (kcc < cst + 16); const float bv = rp[clampi(kcc - qcol + 15, 0, 30)]; mbv[q8] = ok ? bv : -2e30f; }
.Lst_na:
	v_readlane_b32 s2, v254, 18
	v_readfirstlane_b32 s49, v144
	s_ashr_i32 s48, s49, 6
	s_add_i32 s84, s2, s48
	s_cmpk_gt_i32 s84, 0xbff
	v_readfirstlane_b32 s2, v0
	s_cbranch_scc1 .LBB0_418
	s_load_dwordx2 s[44:45], s[92:93], s2 offset:0x58
	s_load_dwordx2 s[46:47], s[92:93], s2 offset:0xa8
	s_mul_i32 s2, s48, 0x3000
	v_and_b32_e32 v2, 48, v144
	v_mov_b32_e32 v3, v1
	s_add_i32 s85, s2, 0
	v_and_b32_e32 v114, 15, v144
	s_waitcnt lgkmcnt(0)
	v_lshl_add_u64 v[4:5], s[46:47], 0, v[2:3]
	s_mov_b64 s[6:7], 0x7f00400
	s_add_u32 s2, s46, 0x7f00000
	v_lshl_add_u64 v[116:117], v[4:5], 0, s[6:7]
	v_mul_u32_u24_e32 v4, 0x90, v114
	v_bfe_u32 v6, v144, 4, 2
	s_addc_u32 s3, s47, 0
	v_add3_u32 v143, s85, v4, v2
	v_subrev_co_u32_e32 v4, vcc, 8, v114
	s_add_u32 s86, s46, 0xa300000
	v_min_u32_e32 v4, 48, v4
	v_lshlrev_b32_e32 v124, 2, v6
	s_addc_u32 s87, s47, 0
	v_cndmask_b32_e64 v8, v4, 0, vcc
	v_or_b32_e32 v170, 16, v124
	s_add_u32 s76, s46, 0x5b00000
	v_add_u32_e32 v9, 16, v8
	v_cmp_lt_u32_e64 s[8:9], v124, v8
	v_cmp_ge_u32_e32 vcc, v170, v8
	v_or_b32_e32 v172, 17, v124
	s_addc_u32 s77, s47, 0
	s_and_b64 s[14:15], vcc, s[8:9]
	v_cmp_ge_u32_e32 vcc, v172, v8
	v_cmp_lt_u32_e64 s[16:17], v172, v9
	v_or_b32_e32 v174, 18, v124
	v_and_b32_e32 v7, 63, v144
	v_or_b32_e32 v167, 1, v124
	v_or_b32_e32 v168, 3, v124
	v_or_b32_e32 v169, 2, v124
	v_sub_u32_e32 v10, v170, v114
	s_and_b64 s[16:17], vcc, s[16:17]
	v_cmp_ge_u32_e32 vcc, v174, v8
	v_cmp_lt_u32_e64 s[18:19], v174, v9
	v_or_b32_e32 v176, 19, v124
	v_or_b32_e32 v5, 48, v7
	v_cmp_lt_u32_e64 s[6:7], v167, v8
	v_cmp_lt_u32_e64 s[10:11], v168, v8
	v_cmp_lt_u32_e64 s[12:13], v169, v8
	v_min_u32_e32 v171, 15, v10
	v_sub_u32_e32 v10, v172, v114
	s_and_b64 s[18:19], vcc, s[18:19]
	v_cmp_ge_u32_e32 vcc, v176, v8
	v_sub_u32_e32 v8, v176, v114
	v_min_u32_e32 v173, 15, v10
	v_sub_u32_e32 v10, v174, v114
	v_min_u32_e32 v177, 15, v8
	v_add_u32_e32 v8, -8, v5
	v_min_u32_e32 v175, 15, v10
	v_min_u32_e32 v8, 48, v8
	v_or_b32_e32 v10, 32, v124
	v_cmp_lt_u32_e64 s[22:23], v10, v8
	v_sub_u32_e32 v10, v10, v5
	v_sub_u32_e64 v183, v10, -15 clamp
	v_or_b32_e32 v10, 33, v124
	v_cmp_lt_u32_e64 s[24:25], v10, v8
	v_sub_u32_e32 v10, v10, v5
	v_sub_u32_e64 v207, v10, -15 clamp
	v_or_b32_e32 v10, 34, v124
	v_cmp_lt_u32_e64 s[26:27], v10, v8
	v_sub_u32_e32 v10, v10, v5
	s_bfe_u32 s49, s49, 0x30006
	v_sub_u32_e64 v208, v10, -15 clamp
	v_or_b32_e32 v10, 35, v124
	v_lshl_add_u64 v[2:3], s[2:3], 0, v[2:3]
	s_lshl_b32 s64, s49, 7
	v_cmp_lt_u32_e64 s[20:21], v176, v9
	v_add_u32_e32 v9, 16, v8
	v_cmp_lt_u32_e64 s[28:29], v10, v8
	v_sub_u32_e32 v8, v10, v5
	v_lshl_add_u64 v[126:127], v[2:3], 0, s[64:65]
	v_lshrrev_b32_e32 v2, 1, v144
	v_sub_u32_e64 v209, v8, -15 clamp
	v_or_b32_e32 v8, 49, v124
	v_or_b32_e32 v10, 48, v124
	v_and_b32_e32 v2, 24, v2
	v_mov_b32_e32 v3, v1
	v_lshlrev_b32_e32 v0, 3, v6
	v_sub_u32_e32 v210, v10, v5
	v_cmp_lt_u32_e64 s[30:31], v8, v9
	v_cmp_lt_u32_e64 s[34:35], v10, v9
	v_or_b32_e32 v8, 51, v124
	v_or_b32_e32 v10, 50, v124
	s_mul_i32 s50, s49, 0x1d1
	v_lshl_add_u64 v[132:133], s[46:47], 0, v[2:3]
	v_readlane_b32 s46, v254, 19
	v_mul_u32_u24_e32 v118, 0x1200, v114
	v_or_b32_e32 v4, 0x800, v124
	v_or_b32_e32 v6, 0x810, v124
	v_cmp_lt_u32_e64 s[40:41], v8, v9
	v_cmp_lt_u32_e64 s[42:43], v10, v9
	v_lshl_add_u64 v[8:9], s[76:77], 0, v[0:1]
	s_add_i32 s89, s46, s48
	s_lshl_b32 s46, s48, 6
	v_readlane_b32 s47, v254, 21
	v_add_lshl_u32 v2, s50, v7, 2
	v_mov_b32_e32 v119, v1
	v_mul_u32_u24_e32 v120, 0x1200, v5
	v_mov_b32_e32 v121, v1
	v_or_b32_e32 v125, 0x4000, v114
	v_mov_b32_e32 v115, v1
	v_mul_hi_u32_u24_e32 v123, 0x1200, v114
	v_mov_b32_e32 v122, v118
	v_bitop3_b32 v145, v144, 15, v144 bitop3:0xc
	s_and_b64 s[20:21], vcc, s[20:21]
	v_or_b32_e32 v178, 16, v114
	v_add_u32_e32 v179, 8, v114
	v_add_u32_e32 v180, 24, v114
	v_or_b32_e32 v181, 32, v114
	v_add_u32_e32 v182, 40, v114
	v_sub_u32_e32 v211, v10, v5
	s_lshl_b32 s88, s49, 6
	v_lshl_add_u64 v[128:129], v[116:117], 0, s[64:65]
	v_lshl_add_u64 v[130:131], v[8:9], 0, s[64:65]
	s_add_i32 s90, s47, s46
	v_lshl_add_u32 v212, v7, 2, s85
	v_or_b32_e32 v213, 0xffffffc0, v7
	v_lshl_add_u64 v[134:135], s[44:45], 0, v[2:3]
	v_lshlrev_b32_e32 v136, 1, v0
	v_lshlrev_b32_e32 v146, 1, v4
	v_lshlrev_b32_e32 v148, 1, v6
	s_branch .LBB0_382
	s_nop 0
	s_nop 0
	s_nop 0
	s_nop 0
	s_nop 0
	s_nop 0
	s_nop 0
	s_nop 0
	s_nop 0
	s_nop 0
	s_nop 0
	s_nop 0
	s_nop 0

; #define PG8_STAGE(bufoff, gbase, voff) do { _Pragma("unroll") for (int _i = 0; _i < 2; ++_i) \
;         __builtin_amdgcn_global_load_lds((const unsigned*)((const char*)(gbase) + (voff)[_i]), (PG8_LAS unsigned*)(lds + (bufoff) + ldsw + _i * 8192), 16, 0, 0); } while (0)
; #define PG8_LDA(dst, b, h) do { _Pragma("unroll") for (int m = 0; m < 4; ++m) _Pragma("unroll") for (int k = 0; k < 2; ++k) dst[m][k] = *(const PG8_LAS bf16x8*)(lds + PG8_SA(b, h) + aoff + m * 2048 + k * 1024); } while (0)
; #define PG8_LDB(dst, b, h) do { _Pragma("unroll") for (int n = 0; n < 2; ++n) _Pragma("unroll") for (int k = 0; k < 2; ++k) dst[n][k] = *(const PG8_LAS bf16x8*)(lds + PG8_SB(b, h) + boff + n * 2048 + k * 1024); } while (0)
; #define PG8_MMA(ai, bj, At, Bt) do { __builtin_amdgcn_s_setprio(1); _Pragma("unroll") for (int m = 0; m < 4; ++m) _Pragma("unroll") for (int n = 0; n < 2; ++n) _Pragma("unroll") for (int k = 0; k < 2; ++k) \
;         acc[ai][bj][m][n] = __builtin_amdgcn_mfma_f32_16x16x32_bf16(Bt[n][k], At[m][k], acc[ai][bj][m][n], 0, 0, 0); __builtin_amdgcn_s_setprio(0); } while (0)
; #define PG8_WAIT_V(n) asm volatile("s_waitcnt vmcnt(" #n ")" ::: "memory")
; #define PG8_WAIT_L(n) asm volatile("s_waitcnt lgkmcnt(" #n ")" ::: "memory")
; #define PG8_BAR __builtin_amdgcn_s_barrier()
; #define PG8_SCHED __builtin_amdgcn_sched_barrier(0)
; template <class Epi, class Sched, bool ALIGN_EPI = false, bool SP2 = false>
; __device__ __forceinline__ void gemm_phase(PG8_LAS unsigned char* lds, const Gemm g, const Sched& S, const Epi& E) {
;     ...
;             PG8_LDB(B0, 0, 0); PG8_LDB(B1, 0, 1); PG8_SCHED; PG8_LDA(At, 0, 0); PG8_STAGE(PG8_SA(1, 1), a1 + hstep, voffA);
;             PG8_WAIT_V(8); PG8_WAIT_L(0); PG8_BAR; PG8_MMA(0, 0, At, B0); PG8_MMA(0, 1, At, B1); PG8_BAR; PG8_SCHED;
;             PG8_LDA(At, 0, 1); PG8_STAGE(PG8_SB(0, 0), b2, voffB); PG8_STAGE(PG8_SB(0, 1), b2 + hstep, voffB); PG8_STAGE(PG8_SA(0, 0), a2, voffA);
.Lpeel_r:
	s_add_i32 s82, s76, 2
	s_add_u32 s83, s48, 0x80
	s_addc_u32 s77, s49, 0
	s_add_i32 s59, 0, 0x10000
	s_cmp_eq_u32 s72, s76
	s_cselect_b32 s77, s9, s77
	s_cselect_b32 s76, s8, s83
	v_add_u32_e32 v136, s59, v147
	s_cselect_b32 vcc_hi, s47, s81
	s_cselect_b32 vcc_lo, s46, s80
	s_add_i32 s83, 0, 0x14000
	ds_read_b128 v[148:151], v136
	ds_read_b128 v[152:155], v136 offset:1024
	ds_read_b128 v[156:159], v136 offset:2048
	ds_read_b128 v[160:163], v136 offset:3072
	v_add_u32_e32 v136, s83, v147
	ds_read_b128 v[166:169], v136
	ds_read_b128 v[170:173], v136 offset:1024
	ds_read_b128 v[174:177], v136 offset:2048
	ds_read_b128 v[178:181], v136 offset:3072
	v_lshl_add_u64 v[136:137], s[48:49], 0, v[132:133]
	s_add_i32 m0, s94, 0xc000
	ds_read_b128 v[202:205], v165
	ds_read_b128 v[208:211], v165 offset:1024
	ds_read_b128 v[212:215], v165 offset:2048
	ds_read_b128 v[216:219], v165 offset:3072
	ds_read_b128 v[220:223], v165 offset:4096
	ds_read_b128 v[224:227], v165 offset:5120
	ds_read_b128 v[228:231], v165 offset:6144
	ds_read_b128 v[232:235], v165 offset:7168
	global_load_lds_dwordx4 v[136:137], off
	v_lshl_add_u64 v[136:137], s[48:49], 0, v[134:135]
	s_add_i32 m0, s94, 0xe000
	s_nop 0
	global_load_lds_dwordx4 v[136:137], off
	s_waitcnt vmcnt(8)
	s_waitcnt lgkmcnt(0)
	s_barrier
	s_setprio 1
	s_waitcnt lgkmcnt(0)
	v_mfma_f32_16x16x32_bf16 v[126:129], v[148:151], v[202:205], 0
	v_mfma_f32_16x16x32_bf16 v[122:125], v[156:159], v[202:205], 0
	v_mfma_f32_16x16x32_bf16 v[110:113], v[148:151], v[212:215], 0
	v_mfma_f32_16x16x32_bf16 v[106:109], v[156:159], v[212:215], 0
	v_mfma_f32_16x16x32_bf16 v[94:97], v[148:151], v[220:223], 0
	v_mfma_f32_16x16x32_bf16 v[90:93], v[156:159], v[220:223], 0
	v_mfma_f32_16x16x32_bf16 v[78:81], v[148:151], v[228:231], 0
	v_mfma_f32_16x16x32_bf16 v[74:77], v[156:159], v[228:231], 0
	v_mfma_f32_16x16x32_bf16 v[126:129], v[152:155], v[208:211], v[126:129]
	v_mfma_f32_16x16x32_bf16 v[122:125], v[160:163], v[208:211], v[122:125]
	v_mfma_f32_16x16x32_bf16 v[110:113], v[152:155], v[216:219], v[110:113]
	v_mfma_f32_16x16x32_bf16 v[106:109], v[160:163], v[216:219], v[106:109]
	v_mfma_f32_16x16x32_bf16 v[94:97], v[152:155], v[224:227], v[94:97]
	v_mfma_f32_16x16x32_bf16 v[90:93], v[160:163], v[224:227], v[90:93]
	v_mfma_f32_16x16x32_bf16 v[78:81], v[152:155], v[232:235], v[78:81]
	v_mfma_f32_16x16x32_bf16 v[74:77], v[160:163], v[232:235], v[74:77]
	s_setprio 0
	s_setprio 1
	v_mfma_f32_16x16x32_bf16 v[118:121], v[166:169], v[202:205], 0
	v_mfma_f32_16x16x32_bf16 v[114:117], v[174:177], v[202:205], 0
	v_mfma_f32_16x16x32_bf16 v[102:105], v[166:169], v[212:215], 0
	v_mfma_f32_16x16x32_bf16 v[98:101], v[174:177], v[212:215], 0
	v_mfma_f32_16x16x32_bf16 v[86:89], v[166:169], v[220:223], 0
	v_mfma_f32_16x16x32_bf16 v[82:85], v[174:177], v[220:223], 0
	v_mfma_f32_16x16x32_bf16 v[70:73], v[166:169], v[228:231], 0
	v_mfma_f32_16x16x32_bf16 v[66:69], v[174:177], v[228:231], 0
	v_mfma_f32_16x16x32_bf16 v[118:121], v[170:173], v[208:211], v[118:121]
	v_mfma_f32_16x16x32_bf16 v[114:117], v[178:181], v[208:211], v[114:117]
	v_mfma_f32_16x16x32_bf16 v[102:105], v[170:173], v[216:219], v[102:105]
	v_mfma_f32_16x16x32_bf16 v[98:101], v[178:181], v[216:219], v[98:101]
	v_mfma_f32_16x16x32_bf16 v[86:89], v[170:173], v[224:227], v[86:89]
	v_mfma_f32_16x16x32_bf16 v[82:85], v[178:181], v[224:227], v[82:85]
	v_mfma_f32_16x16x32_bf16 v[70:73], v[170:173], v[232:235], v[70:73]
	v_mfma_f32_16x16x32_bf16 v[66:69], v[178:181], v[232:235], v[66:69]
	s_setprio 0
	s_barrier
	s_add_i32 s59, s59, s93
	v_lshl_add_u64 v[136:137], vcc, 0, v[0:1]
	s_mov_b32 m0, s59
	ds_read_b128 v[202:205], v165 offset:16384
	ds_read_b128 v[208:211], v165 offset:17408
	ds_read_b128 v[212:215], v165 offset:18432
	ds_read_b128 v[216:219], v165 offset:19456
	ds_read_b128 v[220:223], v165 offset:20480
	ds_read_b128 v[224:227], v165 offset:21504
	ds_read_b128 v[228:231], v165 offset:22528
	ds_read_b128 v[232:235], v165 offset:23552
	global_load_lds_dwordx4 v[136:137], off
	s_add_i32 m0, s59, 0x2000
	v_lshl_add_u64 v[144:145], vcc, 0, v[130:131]
	s_add_u32 vcc_lo, vcc_lo, s10
	s_addc_u32 vcc_hi, vcc_hi, 0
	s_add_i32 s59, s83, s93
	global_load_lds_dwordx4 v[144:145], off
	v_lshl_add_u64 v[182:183], vcc, 0, v[0:1]
	s_mov_b32 m0, s59
	v_lshl_add_u64 v[236:237], vcc, 0, v[130:131]
	global_load_lds_dwordx4 v[182:183], off
	s_add_i32 m0, s59, 0x2000
	v_lshl_add_u64 v[238:239], s[76:77], 0, v[0:1]
	global_load_lds_dwordx4 v[236:237], off
	s_mov_b32 m0, s94
	v_lshl_add_u64 v[240:241], s[76:77], 0, v[130:131]
	global_load_lds_dwordx4 v[238:239], off
	s_mov_b32 m0, s95
	s_nop 0
	global_load_lds_dwordx4 v[240:241], off
	s_waitcnt vmcnt(8)
	s_waitcnt lgkmcnt(0)
	s_barrier
; #define PG8_STAGE(bufoff, gbase, voff) do { _Pragma("unroll") for (int _i = 0; _i < 2; ++_i) \
;         __builtin_amdgcn_global_load_lds((const unsigned*)((const char*)(gbase) + (voff)[_i]), (PG8_LAS unsigned*)(lds + (bufoff) + ldsw + _i * 8192), 16, 0, 0); } while (0)
; #define PG8_LDA(dst, b, h) do { _Pragma("unroll") for (int m = 0; m < 4; ++m) _Pragma("unroll") for (int k = 0; k < 2; ++k) dst[m][k] = *(const PG8_LAS bf16x8*)(lds + PG8_SA(b, h) + aoff + m * 2048 + k * 1024); } while (0)
; #define PG8_LDB(dst, b, h) do { _Pragma("unroll") for (int n = 0; n < 2; ++n) _Pragma("unroll") for (int k = 0; k < 2; ++k) dst[n][k] = *(const PG8_LAS bf16x8*)(lds + PG8_SB(b, h) + boff + n * 2048 + k * 1024); } while (0)
; #define PG8_MMA(ai, bj, At, Bt) do { __builtin_amdgcn_s_setprio(1); _Pragma("unroll") for (int m = 0; m < 4; ++m) _Pragma("unroll") for (int n = 0; n < 2; ++n) _Pragma("unroll") for (int k = 0; k < 2; ++k) \
;         acc[ai][bj][m][n] = __builtin_amdgcn_mfma_f32_16x16x32_bf16(Bt[n][k], At[m][k], acc[ai][bj][m][n], 0, 0, 0); __builtin_amdgcn_s_setprio(0); } while (0)
; #define PG8_WAIT_V(n) asm volatile("s_waitcnt vmcnt(" #n ")" ::: "memory")
; #define PG8_WAIT_L(n) asm volatile("s_waitcnt lgkmcnt(" #n ")" ::: "memory")
; #define PG8_BAR __builtin_amdgcn_s_barrier()
; #define PG8_SCHED __builtin_amdgcn_sched_barrier(0)
; template <class Epi, class Sched, bool ALIGN_EPI = false, bool SP2 = false>
; __device__ __forceinline__ void gemm_phase(PG8_LAS unsigned char* lds, const Gemm g, const Sched& S, const Epi& E) {
;     ...
;             PG8_WAIT_V(8); PG8_WAIT_L(0); PG8_BAR; PG8_MMA(1, 0, At, B0); PG8_MMA(1, 1, At, B1); PG8_BAR; PG8_SCHED;
;             PG8_LDB(B0, 1, 0); PG8_LDB(B1, 1, 1); PG8_SCHED; PG8_LDA(At, 1, 0); PG8_STAGE(PG8_SA(0, 1), a2 + hstep, voffA);
;             PG8_WAIT_V(8); PG8_WAIT_L(0); PG8_BAR; PG8_MMA(0, 0, At, B0); PG8_MMA(0, 1, At, B1); PG8_BAR; PG8_SCHED;
	s_setprio 1
	s_waitcnt lgkmcnt(0)
	v_mfma_f32_16x16x32_bf16 v[62:65], v[148:151], v[202:205], 0
	v_mfma_f32_16x16x32_bf16 v[58:61], v[156:159], v[202:205], 0
	v_mfma_f32_16x16x32_bf16 v[46:49], v[148:151], v[212:215], 0
	v_mfma_f32_16x16x32_bf16 v[42:45], v[156:159], v[212:215], 0
	v_mfma_f32_16x16x32_bf16 v[30:33], v[148:151], v[220:223], 0
	v_mfma_f32_16x16x32_bf16 v[26:29], v[156:159], v[220:223], 0
	v_mfma_f32_16x16x32_bf16 v[14:17], v[148:151], v[228:231], 0
	v_mfma_f32_16x16x32_bf16 v[10:13], v[156:159], v[228:231], 0
	v_mfma_f32_16x16x32_bf16 v[62:65], v[152:155], v[208:211], v[62:65]
	v_mfma_f32_16x16x32_bf16 v[58:61], v[160:163], v[208:211], v[58:61]
	v_mfma_f32_16x16x32_bf16 v[46:49], v[152:155], v[216:219], v[46:49]
	v_mfma_f32_16x16x32_bf16 v[42:45], v[160:163], v[216:219], v[42:45]
	v_mfma_f32_16x16x32_bf16 v[30:33], v[152:155], v[224:227], v[30:33]
	v_mfma_f32_16x16x32_bf16 v[26:29], v[160:163], v[224:227], v[26:29]
	v_mfma_f32_16x16x32_bf16 v[14:17], v[152:155], v[232:235], v[14:17]
	v_mfma_f32_16x16x32_bf16 v[10:13], v[160:163], v[232:235], v[10:13]
	s_setprio 0
	s_setprio 1
	v_mfma_f32_16x16x32_bf16 v[54:57], v[166:169], v[202:205], 0
	v_mfma_f32_16x16x32_bf16 v[50:53], v[174:177], v[202:205], 0
	v_mfma_f32_16x16x32_bf16 v[38:41], v[166:169], v[212:215], 0
	v_mfma_f32_16x16x32_bf16 v[34:37], v[174:177], v[212:215], 0
	v_mfma_f32_16x16x32_bf16 v[22:25], v[166:169], v[220:223], 0
	v_mfma_f32_16x16x32_bf16 v[18:21], v[174:177], v[220:223], 0
	v_mfma_f32_16x16x32_bf16 v[6:9], v[166:169], v[228:231], 0
	v_mfma_f32_16x16x32_bf16 v[2:5], v[174:177], v[228:231], 0
	v_mfma_f32_16x16x32_bf16 v[54:57], v[170:173], v[208:211], v[54:57]
	v_mfma_f32_16x16x32_bf16 v[50:53], v[178:181], v[208:211], v[50:53]
	v_mfma_f32_16x16x32_bf16 v[38:41], v[170:173], v[216:219], v[38:41]
	v_mfma_f32_16x16x32_bf16 v[34:37], v[178:181], v[216:219], v[34:37]
	v_mfma_f32_16x16x32_bf16 v[22:25], v[170:173], v[224:227], v[22:25]
	v_mfma_f32_16x16x32_bf16 v[18:21], v[178:181], v[224:227], v[18:21]
	v_mfma_f32_16x16x32_bf16 v[6:9], v[170:173], v[232:235], v[6:9]
	v_mfma_f32_16x16x32_bf16 v[2:5], v[178:181], v[232:235], v[2:5]
	s_setprio 0
	s_barrier
	s_add_i32 s59, 0, 0x18000
	s_add_i32 s83, 0, 0x1c000
	v_add_u32_e32 v160, s59, v147
	v_add_u32_e32 v178, s83, v147
	ds_read_b128 v[148:151], v160
	ds_read_b128 v[152:155], v160 offset:1024
	ds_read_b128 v[156:159], v160 offset:2048
	ds_read_b128 v[160:163], v160 offset:3072
	ds_read_b128 v[166:169], v178
	ds_read_b128 v[170:173], v178 offset:1024
	ds_read_b128 v[174:177], v178 offset:2048
	ds_read_b128 v[178:181], v178 offset:3072
	s_add_u32 s76, s76, s10
	s_addc_u32 s77, s77, 0
	s_mov_b32 m0, s84
	v_lshl_add_u64 v[242:243], s[76:77], 0, v[0:1]
	ds_read_b128 v[202:205], v165 offset:32768
	ds_read_b128 v[208:211], v165 offset:33792
	ds_read_b128 v[212:215], v165 offset:34816
	ds_read_b128 v[216:219], v165 offset:35840
	ds_read_b128 v[220:223], v165 offset:36864
	ds_read_b128 v[224:227], v165 offset:37888
	ds_read_b128 v[228:231], v165 offset:38912
	ds_read_b128 v[232:235], v165 offset:39936
	global_load_lds_dwordx4 v[242:243], off
	v_lshl_add_u64 v[242:243], s[76:77], 0, v[130:131]
	s_mov_b32 m0, s74
	s_nop 0
	global_load_lds_dwordx4 v[242:243], off
	s_waitcnt vmcnt(8)
	s_waitcnt lgkmcnt(0)
	s_barrier
	s_setprio 1
	s_waitcnt lgkmcnt(0)
	v_mfma_f32_16x16x32_bf16 v[126:129], v[148:151], v[202:205], v[126:129]
	v_mfma_f32_16x16x32_bf16 v[122:125], v[156:159], v[202:205], v[122:125]
	v_mfma_f32_16x16x32_bf16 v[110:113], v[148:151], v[212:215], v[110:113]
	v_mfma_f32_16x16x32_bf16 v[106:109], v[156:159], v[212:215], v[106:109]
	v_mfma_f32_16x16x32_bf16 v[94:97], v[148:151], v[220:223], v[94:97]
	v_mfma_f32_16x16x32_bf16 v[90:93], v[156:159], v[220:223], v[90:93]
	v_mfma_f32_16x16x32_bf16 v[78:81], v[148:151], v[228:231], v[78:81]
	v_mfma_f32_16x16x32_bf16 v[74:77], v[156:159], v[228:231], v[74:77]
	v_mfma_f32_16x16x32_bf16 v[126:129], v[152:155], v[208:211], v[126:129]
	v_mfma_f32_16x16x32_bf16 v[122:125], v[160:163], v[208:211], v[122:125]
	v_mfma_f32_16x16x32_bf16 v[110:113], v[152:155], v[216:219], v[110:113]
	v_mfma_f32_16x16x32_bf16 v[106:109], v[160:163], v[216:219], v[106:109]
	v_mfma_f32_16x16x32_bf16 v[94:97], v[152:155], v[224:227], v[94:97]
	v_mfma_f32_16x16x32_bf16 v[90:93], v[160:163], v[224:227], v[90:93]
	v_mfma_f32_16x16x32_bf16 v[78:81], v[152:155], v[232:235], v[78:81]
	v_mfma_f32_16x16x32_bf16 v[74:77], v[160:163], v[232:235], v[74:77]
	s_setprio 0
	s_setprio 1
	v_mfma_f32_16x16x32_bf16 v[118:121], v[166:169], v[202:205], v[118:121]
	v_mfma_f32_16x16x32_bf16 v[114:117], v[174:177], v[202:205], v[114:117]
	v_mfma_f32_16x16x32_bf16 v[102:105], v[166:169], v[212:215], v[102:105]
	v_mfma_f32_16x16x32_bf16 v[98:101], v[174:177], v[212:215], v[98:101]
	v_mfma_f32_16x16x32_bf16 v[86:89], v[166:169], v[220:223], v[86:89]
	v_mfma_f32_16x16x32_bf16 v[82:85], v[174:177], v[220:223], v[82:85]
	v_mfma_f32_16x16x32_bf16 v[70:73], v[166:169], v[228:231], v[70:73]
	v_mfma_f32_16x16x32_bf16 v[66:69], v[174:177], v[228:231], v[66:69]
	v_mfma_f32_16x16x32_bf16 v[118:121], v[170:173], v[208:211], v[118:121]
	v_mfma_f32_16x16x32_bf16 v[114:117], v[178:181], v[208:211], v[114:117]
	v_mfma_f32_16x16x32_bf16 v[102:105], v[170:173], v[216:219], v[102:105]
	v_mfma_f32_16x16x32_bf16 v[98:101], v[178:181], v[216:219], v[98:101]
	v_mfma_f32_16x16x32_bf16 v[86:89], v[170:173], v[224:227], v[86:89]
	v_mfma_f32_16x16x32_bf16 v[82:85], v[178:181], v[224:227], v[82:85]
	v_mfma_f32_16x16x32_bf16 v[70:73], v[170:173], v[232:235], v[70:73]
	v_mfma_f32_16x16x32_bf16 v[66:69], v[178:181], v[232:235], v[66:69]
	s_setprio 0
	s_barrier
; #define PG8_STAGE(bufoff, gbase, voff) do { _Pragma("unroll") for (int _i = 0; _i < 2; ++_i) \
;         __builtin_amdgcn_global_load_lds((const unsigned*)((const char*)(gbase) + (voff)[_i]), (PG8_LAS unsigned*)(lds + (bufoff) + ldsw + _i * 8192), 16, 0, 0); } while (0)
; #define PG8_LDA(dst, b, h) do { _Pragma("unroll") for (int m = 0; m < 4; ++m) _Pragma("unroll") for (int k = 0; k < 2; ++k) dst[m][k] = *(const PG8_LAS bf16x8*)(lds + PG8_SA(b, h) + aoff + m * 2048 + k * 1024); } while (0)
; #define PG8_LDB(dst, b, h) do { _Pragma("unroll") for (int n = 0; n < 2; ++n) _Pragma("unroll") for (int k = 0; k < 2; ++k) dst[n][k] = *(const PG8_LAS bf16x8*)(lds + PG8_SB(b, h) + boff + n * 2048 + k * 1024); } while (0)
; #define PG8_MMA(ai, bj, At, Bt) do { __builtin_amdgcn_s_setprio(1); _Pragma("unroll") for (int m = 0; m < 4; ++m) _Pragma("unroll") for (int n = 0; n < 2; ++n) _Pragma("unroll") for (int k = 0; k < 2; ++k) \
;         acc[ai][bj][m][n] = __builtin_amdgcn_mfma_f32_16x16x32_bf16(Bt[n][k], At[m][k], acc[ai][bj][m][n], 0, 0, 0); __builtin_amdgcn_s_setprio(0); } while (0)
; #define PG8_WAIT_V(n) asm volatile("s_waitcnt vmcnt(" #n ")" ::: "memory")
; #define PG8_WAIT_L(n) asm volatile("s_waitcnt lgkmcnt(" #n ")" ::: "memory")
; #define PG8_BAR __builtin_amdgcn_s_barrier()
; #define PG8_SCHED __builtin_amdgcn_sched_barrier(0)
; template <class Epi, class Sched, bool ALIGN_EPI = false, bool SP2 = false>
; __device__ __forceinline__ void gemm_phase(PG8_LAS unsigned char* lds, const Gemm g, const Sched& S, const Epi& E) {
;     ...
;             PG8_LDB(B0, 0, 0); PG8_LDB(B1, 0, 1); PG8_SCHED; PG8_LDA(At, 0, 0); PG8_STAGE(PG8_SA(1, 1), a1 + hstep, voffA);
;     ...
;             PG8_LDA(At, 1, 1); PG8_STAGE(PG8_SB(1, 0), b3, voffB); PG8_STAGE(PG8_SB(1, 1), b3 + hstep, voffB); PG8_STAGE(PG8_SA(1, 0), a3, voffA);
;             PG8_WAIT_V(8); PG8_WAIT_L(0); PG8_BAR; PG8_MMA(1, 0, At, B0); PG8_MMA(1, 1, At, B1); PG8_BAR; PG8_SCHED;
	s_add_i32 s59, s59, s93
	v_lshl_add_u64 v[136:137], v[136:137], 0, s[66:67]
	s_mov_b32 m0, s59
	ds_read_b128 v[202:205], v165 offset:49152
	ds_read_b128 v[208:211], v165 offset:50176
	ds_read_b128 v[212:215], v165 offset:51200
	ds_read_b128 v[216:219], v165 offset:52224
	ds_read_b128 v[220:223], v165 offset:53248
	ds_read_b128 v[224:227], v165 offset:54272
	ds_read_b128 v[228:231], v165 offset:55296
	ds_read_b128 v[232:235], v165 offset:56320
	global_load_lds_dwordx4 v[136:137], off
	v_lshl_add_u64 v[136:137], v[144:145], 0, s[66:67]
	s_add_i32 m0, s59, 0x2000
	s_add_i32 s59, s83, s93
	global_load_lds_dwordx4 v[136:137], off
	v_lshl_add_u64 v[136:137], v[182:183], 0, s[66:67]
	s_mov_b32 m0, s59
	s_nop 0
	global_load_lds_dwordx4 v[136:137], off
	v_lshl_add_u64 v[136:137], v[236:237], 0, s[66:67]
	s_add_i32 m0, s59, 0x2000
	s_nop 0
	global_load_lds_dwordx4 v[136:137], off
	v_lshl_add_u64 v[136:137], v[238:239], 0, s[66:67]
	s_mov_b32 m0, s73
	s_nop 0
	global_load_lds_dwordx4 v[136:137], off
	v_lshl_add_u64 v[136:137], v[240:241], 0, s[66:67]
	s_mov_b32 m0, s50
	s_nop 0
	global_load_lds_dwordx4 v[136:137], off
	s_waitcnt vmcnt(8)
	s_waitcnt lgkmcnt(0)
	s_barrier
	s_setprio 1
	s_waitcnt lgkmcnt(0)
	v_mfma_f32_16x16x32_bf16 v[62:65], v[148:151], v[202:205], v[62:65]
	v_mfma_f32_16x16x32_bf16 v[58:61], v[156:159], v[202:205], v[58:61]
	v_mfma_f32_16x16x32_bf16 v[46:49], v[148:151], v[212:215], v[46:49]
	v_mfma_f32_16x16x32_bf16 v[42:45], v[156:159], v[212:215], v[42:45]
	v_mfma_f32_16x16x32_bf16 v[30:33], v[148:151], v[220:223], v[30:33]
	v_mfma_f32_16x16x32_bf16 v[26:29], v[156:159], v[220:223], v[26:29]
	v_mfma_f32_16x16x32_bf16 v[14:17], v[148:151], v[228:231], v[14:17]
	v_mfma_f32_16x16x32_bf16 v[10:13], v[156:159], v[228:231], v[10:13]
	v_mfma_f32_16x16x32_bf16 v[62:65], v[152:155], v[208:211], v[62:65]
	v_mfma_f32_16x16x32_bf16 v[58:61], v[160:163], v[208:211], v[58:61]
	v_mfma_f32_16x16x32_bf16 v[46:49], v[152:155], v[216:219], v[46:49]
	v_mfma_f32_16x16x32_bf16 v[42:45], v[160:163], v[216:219], v[42:45]
	v_mfma_f32_16x16x32_bf16 v[30:33], v[152:155], v[224:227], v[30:33]
	v_mfma_f32_16x16x32_bf16 v[26:29], v[160:163], v[224:227], v[26:29]
	v_mfma_f32_16x16x32_bf16 v[14:17], v[152:155], v[232:235], v[14:17]
	v_mfma_f32_16x16x32_bf16 v[10:13], v[160:163], v[232:235], v[10:13]
	s_setprio 0
	s_setprio 1
	v_mfma_f32_16x16x32_bf16 v[54:57], v[166:169], v[202:205], v[54:57]
	v_mfma_f32_16x16x32_bf16 v[50:53], v[174:177], v[202:205], v[50:53]
	v_mfma_f32_16x16x32_bf16 v[38:41], v[166:169], v[212:215], v[38:41]
	v_mfma_f32_16x16x32_bf16 v[34:37], v[174:177], v[212:215], v[34:37]
	v_mfma_f32_16x16x32_bf16 v[22:25], v[166:169], v[220:223], v[22:25]
	v_mfma_f32_16x16x32_bf16 v[18:21], v[174:177], v[220:223], v[18:21]
	v_mfma_f32_16x16x32_bf16 v[6:9], v[166:169], v[228:231], v[6:9]
	v_mfma_f32_16x16x32_bf16 v[2:5], v[174:177], v[228:231], v[2:5]
	v_mfma_f32_16x16x32_bf16 v[54:57], v[170:173], v[208:211], v[54:57]
	v_mfma_f32_16x16x32_bf16 v[50:53], v[178:181], v[208:211], v[50:53]
	v_mfma_f32_16x16x32_bf16 v[38:41], v[170:173], v[216:219], v[38:41]
	v_mfma_f32_16x16x32_bf16 v[34:37], v[178:181], v[216:219], v[34:37]
	v_mfma_f32_16x16x32_bf16 v[22:25], v[170:173], v[224:227], v[22:25]
	v_mfma_f32_16x16x32_bf16 v[18:21], v[178:181], v[224:227], v[18:21]
	v_mfma_f32_16x16x32_bf16 v[6:9], v[170:173], v[232:235], v[6:9]
	v_mfma_f32_16x16x32_bf16 v[2:5], v[178:181], v[232:235], v[2:5]
	s_setprio 0
	s_barrier
	s_add_u32 s48, s48, 0x100
	s_addc_u32 s49, s49, 0
	s_add_u32 s80, s80, 0x100
	s_addc_u32 s81, s81, 0
	s_cmp_ge_u32 s82, s79
	s_mov_b32 s76, s82
	s_cbranch_scc0 .LBB0_849
	s_branch .Lkq_exit
	s_nop 0
	s_nop 0
	s_nop 0
	s_nop 0
.LBB0_849:
	s_add_i32 s82, s76, 2
	s_add_u32 s83, s48, 0x80
	s_addc_u32 s77, s49, 0
	s_add_i32 s59, 0, 0x10000
	s_cmp_eq_u32 s72, s76
	s_cselect_b32 s77, s9, s77
	s_cselect_b32 s76, s8, s83
	v_add_u32_e32 v136, s59, v147
	s_cselect_b32 vcc_hi, s47, s81
	s_cselect_b32 vcc_lo, s46, s80
	s_add_i32 s83, 0, 0x14000
	ds_read_b128 v[148:151], v136
	ds_read_b128 v[152:155], v136 offset:1024
	ds_read_b128 v[156:159], v136 offset:2048
	ds_read_b128 v[160:163], v136 offset:3072
	v_add_u32_e32 v136, s83, v147
	ds_read_b128 v[166:169], v136
	ds_read_b128 v[170:173], v136 offset:1024
	ds_read_b128 v[174:177], v136 offset:2048
	ds_read_b128 v[178:181], v136 offset:3072
	v_lshl_add_u64 v[136:137], s[48:49], 0, v[132:133]
	s_add_i32 m0, s94, 0xc000
	ds_read_b128 v[202:205], v165
	ds_read_b128 v[208:211], v165 offset:1024
	ds_read_b128 v[212:215], v165 offset:2048
	ds_read_b128 v[216:219], v165 offset:3072
	ds_read_b128 v[220:223], v165 offset:4096
	ds_read_b128 v[224:227], v165 offset:5120
	ds_read_b128 v[228:231], v165 offset:6144
	ds_read_b128 v[232:235], v165 offset:7168
	global_load_lds_dwordx4 v[136:137], off
	v_lshl_add_u64 v[136:137], s[48:49], 0, v[134:135]
	s_add_i32 m0, s94, 0xe000
	s_nop 0
	global_load_lds_dwordx4 v[136:137], off
	s_waitcnt vmcnt(8)
	s_waitcnt lgkmcnt(0)
	s_barrier
; #define PG8_STAGE(bufoff, gbase, voff) do { _Pragma("unroll") for (int _i = 0; _i < 2; ++_i) \
;         __builtin_amdgcn_global_load_lds((const unsigned*)((const char*)(gbase) + (voff)[_i]), (PG8_LAS unsigned*)(lds + (bufoff) + ldsw + _i * 8192), 16, 0, 0); } while (0)
; #define PG8_LDA(dst, b, h) do { _Pragma("unroll") for (int m = 0; m < 4; ++m) _Pragma("unroll") for (int k = 0; k < 2; ++k) dst[m][k] = *(const PG8_LAS bf16x8*)(lds + PG8_SA(b, h) + aoff + m * 2048 + k * 1024); } while (0)
; #define PG8_LDB(dst, b, h) do { _Pragma("unroll") for (int n = 0; n < 2; ++n) _Pragma("unroll") for (int k = 0; k < 2; ++k) dst[n][k] = *(const PG8_LAS bf16x8*)(lds + PG8_SB(b, h) + boff + n * 2048 + k * 1024); } while (0)
; #define PG8_MMA(ai, bj, At, Bt) do { __builtin_amdgcn_s_setprio(1); _Pragma("unroll") for (int m = 0; m < 4; ++m) _Pragma("unroll") for (int n = 0; n < 2; ++n) _Pragma("unroll") for (int k = 0; k < 2; ++k) \
;         acc[ai][bj][m][n] = __builtin_amdgcn_mfma_f32_16x16x32_bf16(Bt[n][k], At[m][k], acc[ai][bj][m][n], 0, 0, 0); __builtin_amdgcn_s_setprio(0); } while (0)
; #define PG8_WAIT_V(n) asm volatile("s_waitcnt vmcnt(" #n ")" ::: "memory")
; #define PG8_WAIT_L(n) asm volatile("s_waitcnt lgkmcnt(" #n ")" ::: "memory")
; #define PG8_BAR __builtin_amdgcn_s_barrier()
; #define PG8_SCHED __builtin_amdgcn_sched_barrier(0)
; template <class Epi, class Sched, bool ALIGN_EPI = false, bool SP2 = false>
; __device__ __forceinline__ void gemm_phase(PG8_LAS unsigned char* lds, const Gemm g, const Sched& S, const Epi& E) {
;     ...
;             PG8_WAIT_V(8); PG8_WAIT_L(0); PG8_BAR; PG8_MMA(0, 0, At, B0); PG8_MMA(0, 1, At, B1); PG8_BAR; PG8_SCHED;
;             PG8_LDA(At, 0, 1); PG8_STAGE(PG8_SB(0, 0), b2, voffB); PG8_STAGE(PG8_SB(0, 1), b2 + hstep, voffB); PG8_STAGE(PG8_SA(0, 0), a2, voffA);
;             PG8_WAIT_V(8); PG8_WAIT_L(0); PG8_BAR; PG8_MMA(1, 0, At, B0); PG8_MMA(1, 1, At, B1); PG8_BAR; PG8_SCHED;
;             PG8_LDB(B0, 1, 0); PG8_LDB(B1, 1, 1); PG8_SCHED; PG8_LDA(At, 1, 0); PG8_STAGE(PG8_SA(0, 1), a2 + hstep, voffA);
	s_setprio 1
	s_waitcnt lgkmcnt(0)
	v_mfma_f32_16x16x32_bf16 v[126:129], v[148:151], v[202:205], v[126:129]
	v_mfma_f32_16x16x32_bf16 v[122:125], v[156:159], v[202:205], v[122:125]
	v_mfma_f32_16x16x32_bf16 v[110:113], v[148:151], v[212:215], v[110:113]
	v_mfma_f32_16x16x32_bf16 v[106:109], v[156:159], v[212:215], v[106:109]
	v_mfma_f32_16x16x32_bf16 v[94:97], v[148:151], v[220:223], v[94:97]
	v_mfma_f32_16x16x32_bf16 v[90:93], v[156:159], v[220:223], v[90:93]
	v_mfma_f32_16x16x32_bf16 v[78:81], v[148:151], v[228:231], v[78:81]
	v_mfma_f32_16x16x32_bf16 v[74:77], v[156:159], v[228:231], v[74:77]
	v_mfma_f32_16x16x32_bf16 v[126:129], v[152:155], v[208:211], v[126:129]
	v_mfma_f32_16x16x32_bf16 v[122:125], v[160:163], v[208:211], v[122:125]
	v_mfma_f32_16x16x32_bf16 v[110:113], v[152:155], v[216:219], v[110:113]
	v_mfma_f32_16x16x32_bf16 v[106:109], v[160:163], v[216:219], v[106:109]
	v_mfma_f32_16x16x32_bf16 v[94:97], v[152:155], v[224:227], v[94:97]
	v_mfma_f32_16x16x32_bf16 v[90:93], v[160:163], v[224:227], v[90:93]
	v_mfma_f32_16x16x32_bf16 v[78:81], v[152:155], v[232:235], v[78:81]
	v_mfma_f32_16x16x32_bf16 v[74:77], v[160:163], v[232:235], v[74:77]
	s_setprio 0
	s_setprio 1
	v_mfma_f32_16x16x32_bf16 v[118:121], v[166:169], v[202:205], v[118:121]
	v_mfma_f32_16x16x32_bf16 v[114:117], v[174:177], v[202:205], v[114:117]
	v_mfma_f32_16x16x32_bf16 v[102:105], v[166:169], v[212:215], v[102:105]
	v_mfma_f32_16x16x32_bf16 v[98:101], v[174:177], v[212:215], v[98:101]
	v_mfma_f32_16x16x32_bf16 v[86:89], v[166:169], v[220:223], v[86:89]
	v_mfma_f32_16x16x32_bf16 v[82:85], v[174:177], v[220:223], v[82:85]
	v_mfma_f32_16x16x32_bf16 v[70:73], v[166:169], v[228:231], v[70:73]
	v_mfma_f32_16x16x32_bf16 v[66:69], v[174:177], v[228:231], v[66:69]
	v_mfma_f32_16x16x32_bf16 v[118:121], v[170:173], v[208:211], v[118:121]
	v_mfma_f32_16x16x32_bf16 v[114:117], v[178:181], v[208:211], v[114:117]
	v_mfma_f32_16x16x32_bf16 v[102:105], v[170:173], v[216:219], v[102:105]
	v_mfma_f32_16x16x32_bf16 v[98:101], v[178:181], v[216:219], v[98:101]
	v_mfma_f32_16x16x32_bf16 v[86:89], v[170:173], v[224:227], v[86:89]
	v_mfma_f32_16x16x32_bf16 v[82:85], v[178:181], v[224:227], v[82:85]
	v_mfma_f32_16x16x32_bf16 v[70:73], v[170:173], v[232:235], v[70:73]
	v_mfma_f32_16x16x32_bf16 v[66:69], v[178:181], v[232:235], v[66:69]
	s_setprio 0
	s_barrier
	s_add_i32 s59, s59, s93
	v_lshl_add_u64 v[136:137], vcc, 0, v[0:1]
	s_mov_b32 m0, s59
	ds_read_b128 v[202:205], v165 offset:16384
	ds_read_b128 v[208:211], v165 offset:17408
	ds_read_b128 v[212:215], v165 offset:18432
	ds_read_b128 v[216:219], v165 offset:19456
	ds_read_b128 v[220:223], v165 offset:20480
	ds_read_b128 v[224:227], v165 offset:21504
	ds_read_b128 v[228:231], v165 offset:22528
	ds_read_b128 v[232:235], v165 offset:23552
	global_load_lds_dwordx4 v[136:137], off
	s_add_i32 m0, s59, 0x2000
	v_lshl_add_u64 v[144:145], vcc, 0, v[130:131]
	s_add_u32 vcc_lo, vcc_lo, s10
	s_addc_u32 vcc_hi, vcc_hi, 0
	s_add_i32 s59, s83, s93
	global_load_lds_dwordx4 v[144:145], off
	v_lshl_add_u64 v[182:183], vcc, 0, v[0:1]
	s_mov_b32 m0, s59
	v_lshl_add_u64 v[236:237], vcc, 0, v[130:131]
	global_load_lds_dwordx4 v[182:183], off
	s_add_i32 m0, s59, 0x2000
	v_lshl_add_u64 v[238:239], s[76:77], 0, v[0:1]
	global_load_lds_dwordx4 v[236:237], off
	s_mov_b32 m0, s94
	v_lshl_add_u64 v[240:241], s[76:77], 0, v[130:131]
	global_load_lds_dwordx4 v[238:239], off
	s_mov_b32 m0, s95
	s_nop 0
	global_load_lds_dwordx4 v[240:241], off
	s_waitcnt vmcnt(8)
	s_waitcnt lgkmcnt(0)
	s_barrier
	s_setprio 1
	s_waitcnt lgkmcnt(0)
	v_mfma_f32_16x16x32_bf16 v[62:65], v[148:151], v[202:205], v[62:65]
	v_mfma_f32_16x16x32_bf16 v[58:61], v[156:159], v[202:205], v[58:61]
	v_mfma_f32_16x16x32_bf16 v[46:49], v[148:151], v[212:215], v[46:49]
	v_mfma_f32_16x16x32_bf16 v[42:45], v[156:159], v[212:215], v[42:45]
	v_mfma_f32_16x16x32_bf16 v[30:33], v[148:151], v[220:223], v[30:33]
	v_mfma_f32_16x16x32_bf16 v[26:29], v[156:159], v[220:223], v[26:29]
	v_mfma_f32_16x16x32_bf16 v[14:17], v[148:151], v[228:231], v[14:17]
	v_mfma_f32_16x16x32_bf16 v[10:13], v[156:159], v[228:231], v[10:13]
	v_mfma_f32_16x16x32_bf16 v[62:65], v[152:155], v[208:211], v[62:65]
	v_mfma_f32_16x16x32_bf16 v[58:61], v[160:163], v[208:211], v[58:61]
	v_mfma_f32_16x16x32_bf16 v[46:49], v[152:155], v[216:219], v[46:49]
	v_mfma_f32_16x16x32_bf16 v[42:45], v[160:163], v[216:219], v[42:45]
	v_mfma_f32_16x16x32_bf16 v[30:33], v[152:155], v[224:227], v[30:33]
	v_mfma_f32_16x16x32_bf16 v[26:29], v[160:163], v[224:227], v[26:29]
	v_mfma_f32_16x16x32_bf16 v[14:17], v[152:155], v[232:235], v[14:17]
	v_mfma_f32_16x16x32_bf16 v[10:13], v[160:163], v[232:235], v[10:13]
	s_setprio 0
	s_setprio 1
	v_mfma_f32_16x16x32_bf16 v[54:57], v[166:169], v[202:205], v[54:57]
	v_mfma_f32_16x16x32_bf16 v[50:53], v[174:177], v[202:205], v[50:53]
	v_mfma_f32_16x16x32_bf16 v[38:41], v[166:169], v[212:215], v[38:41]
	v_mfma_f32_16x16x32_bf16 v[34:37], v[174:177], v[212:215], v[34:37]
	v_mfma_f32_16x16x32_bf16 v[22:25], v[166:169], v[220:223], v[22:25]
	v_mfma_f32_16x16x32_bf16 v[18:21], v[174:177], v[220:223], v[18:21]
	v_mfma_f32_16x16x32_bf16 v[6:9], v[166:169], v[228:231], v[6:9]
	v_mfma_f32_16x16x32_bf16 v[2:5], v[174:177], v[228:231], v[2:5]
	v_mfma_f32_16x16x32_bf16 v[54:57], v[170:173], v[208:211], v[54:57]
	v_mfma_f32_16x16x32_bf16 v[50:53], v[178:181], v[208:211], v[50:53]
	v_mfma_f32_16x16x32_bf16 v[38:41], v[170:173], v[216:219], v[38:41]
	v_mfma_f32_16x16x32_bf16 v[34:37], v[178:181], v[216:219], v[34:37]
	v_mfma_f32_16x16x32_bf16 v[22:25], v[170:173], v[224:227], v[22:25]
	v_mfma_f32_16x16x32_bf16 v[18:21], v[178:181], v[224:227], v[18:21]
	v_mfma_f32_16x16x32_bf16 v[6:9], v[170:173], v[232:235], v[6:9]
	v_mfma_f32_16x16x32_bf16 v[2:5], v[178:181], v[232:235], v[2:5]
	s_setprio 0
	s_barrier
; #define PG8_STAGE(bufoff, gbase, voff) do { _Pragma("unroll") for (int _i = 0; _i < 2; ++_i) \
;         __builtin_amdgcn_global_load_lds((const unsigned*)((const char*)(gbase) + (voff)[_i]), (PG8_LAS unsigned*)(lds + (bufoff) + ldsw + _i * 8192), 16, 0, 0); } while (0)
; #define PG8_LDA(dst, b, h) do { _Pragma("unroll") for (int m = 0; m < 4; ++m) _Pragma("unroll") for (int k = 0; k < 2; ++k) dst[m][k] = *(const PG8_LAS bf16x8*)(lds + PG8_SA(b, h) + aoff + m * 2048 + k * 1024); } while (0)
; #define PG8_LDB(dst, b, h) do { _Pragma("unroll") for (int n = 0; n < 2; ++n) _Pragma("unroll") for (int k = 0; k < 2; ++k) dst[n][k] = *(const PG8_LAS bf16x8*)(lds + PG8_SB(b, h) + boff + n * 2048 + k * 1024); } while (0)
; #define PG8_MMA(ai, bj, At, Bt) do { __builtin_amdgcn_s_setprio(1); _Pragma("unroll") for (int m = 0; m < 4; ++m) _Pragma("unroll") for (int n = 0; n < 2; ++n) _Pragma("unroll") for (int k = 0; k < 2; ++k) \
;         acc[ai][bj][m][n] = __builtin_amdgcn_mfma_f32_16x16x32_bf16(Bt[n][k], At[m][k], acc[ai][bj][m][n], 0, 0, 0); __builtin_amdgcn_s_setprio(0); } while (0)
; #define PG8_WAIT_V(n) asm volatile("s_waitcnt vmcnt(" #n ")" ::: "memory")
; #define PG8_WAIT_L(n) asm volatile("s_waitcnt lgkmcnt(" #n ")" ::: "memory")
; #define PG8_BAR __builtin_amdgcn_s_barrier()
; #define PG8_SCHED __builtin_amdgcn_sched_barrier(0)
; template <class Epi, class Sched, bool ALIGN_EPI = false, bool SP2 = false>
; __device__ __forceinline__ void gemm_phase(PG8_LAS unsigned char* lds, const Gemm g, const Sched& S, const Epi& E) {
;     ...
;             PG8_LDB(B0, 1, 0); PG8_LDB(B1, 1, 1); PG8_SCHED; PG8_LDA(At, 1, 0); PG8_STAGE(PG8_SA(0, 1), a2 + hstep, voffA);
;             PG8_WAIT_V(8); PG8_WAIT_L(0); PG8_BAR; PG8_MMA(0, 0, At, B0); PG8_MMA(0, 1, At, B1); PG8_BAR; PG8_SCHED;
	s_add_i32 s59, 0, 0x18000
	s_add_i32 s83, 0, 0x1c000
	v_add_u32_e32 v160, s59, v147
	v_add_u32_e32 v178, s83, v147
	ds_read_b128 v[148:151], v160
	ds_read_b128 v[152:155], v160 offset:1024
	ds_read_b128 v[156:159], v160 offset:2048
	ds_read_b128 v[160:163], v160 offset:3072
	ds_read_b128 v[166:169], v178
	ds_read_b128 v[170:173], v178 offset:1024
	ds_read_b128 v[174:177], v178 offset:2048
	ds_read_b128 v[178:181], v178 offset:3072
	s_add_u32 s76, s76, s10
	s_addc_u32 s77, s77, 0
	s_mov_b32 m0, s84
	v_lshl_add_u64 v[242:243], s[76:77], 0, v[0:1]
	ds_read_b128 v[202:205], v165 offset:32768
	ds_read_b128 v[208:211], v165 offset:33792
	ds_read_b128 v[212:215], v165 offset:34816
	ds_read_b128 v[216:219], v165 offset:35840
	ds_read_b128 v[220:223], v165 offset:36864
	ds_read_b128 v[224:227], v165 offset:37888
	ds_read_b128 v[228:231], v165 offset:38912
	ds_read_b128 v[232:235], v165 offset:39936
	global_load_lds_dwordx4 v[242:243], off
	v_lshl_add_u64 v[242:243], s[76:77], 0, v[130:131]
	s_mov_b32 m0, s74
	s_nop 0
	global_load_lds_dwordx4 v[242:243], off
	s_waitcnt vmcnt(8)
	s_waitcnt lgkmcnt(0)
	s_barrier
	s_setprio 1
	s_waitcnt lgkmcnt(0)
	v_mfma_f32_16x16x32_bf16 v[126:129], v[148:151], v[202:205], v[126:129]
	v_mfma_f32_16x16x32_bf16 v[122:125], v[156:159], v[202:205], v[122:125]
	v_mfma_f32_16x16x32_bf16 v[110:113], v[148:151], v[212:215], v[110:113]
	v_mfma_f32_16x16x32_bf16 v[106:109], v[156:159], v[212:215], v[106:109]
	v_mfma_f32_16x16x32_bf16 v[94:97], v[148:151], v[220:223], v[94:97]
	v_mfma_f32_16x16x32_bf16 v[90:93], v[156:159], v[220:223], v[90:93]
	v_mfma_f32_16x16x32_bf16 v[78:81], v[148:151], v[228:231], v[78:81]
	v_mfma_f32_16x16x32_bf16 v[74:77], v[156:159], v[228:231], v[74:77]
	v_mfma_f32_16x16x32_bf16 v[126:129], v[152:155], v[208:211], v[126:129]
	v_mfma_f32_16x16x32_bf16 v[122:125], v[160:163], v[208:211], v[122:125]
	v_mfma_f32_16x16x32_bf16 v[110:113], v[152:155], v[216:219], v[110:113]
	v_mfma_f32_16x16x32_bf16 v[106:109], v[160:163], v[216:219], v[106:109]
	v_mfma_f32_16x16x32_bf16 v[94:97], v[152:155], v[224:227], v[94:97]
	v_mfma_f32_16x16x32_bf16 v[90:93], v[160:163], v[224:227], v[90:93]
	v_mfma_f32_16x16x32_bf16 v[78:81], v[152:155], v[232:235], v[78:81]
	v_mfma_f32_16x16x32_bf16 v[74:77], v[160:163], v[232:235], v[74:77]
	s_setprio 0
	s_setprio 1
	v_mfma_f32_16x16x32_bf16 v[118:121], v[166:169], v[202:205], v[118:121]
	v_mfma_f32_16x16x32_bf16 v[114:117], v[174:177], v[202:205], v[114:117]
	v_mfma_f32_16x16x32_bf16 v[102:105], v[166:169], v[212:215], v[102:105]
	v_mfma_f32_16x16x32_bf16 v[98:101], v[174:177], v[212:215], v[98:101]
	v_mfma_f32_16x16x32_bf16 v[86:89], v[166:169], v[220:223], v[86:89]
	v_mfma_f32_16x16x32_bf16 v[82:85], v[174:177], v[220:223], v[82:85]
	v_mfma_f32_16x16x32_bf16 v[70:73], v[166:169], v[228:231], v[70:73]
	v_mfma_f32_16x16x32_bf16 v[66:69], v[174:177], v[228:231], v[66:69]
	v_mfma_f32_16x16x32_bf16 v[118:121], v[170:173], v[208:211], v[118:121]
	v_mfma_f32_16x16x32_bf16 v[114:117], v[178:181], v[208:211], v[114:117]
	v_mfma_f32_16x16x32_bf16 v[102:105], v[170:173], v[216:219], v[102:105]
	v_mfma_f32_16x16x32_bf16 v[98:101], v[178:181], v[216:219], v[98:101]
	v_mfma_f32_16x16x32_bf16 v[86:89], v[170:173], v[224:227], v[86:89]
	v_mfma_f32_16x16x32_bf16 v[82:85], v[178:181], v[224:227], v[82:85]
	v_mfma_f32_16x16x32_bf16 v[70:73], v[170:173], v[232:235], v[70:73]
	v_mfma_f32_16x16x32_bf16 v[66:69], v[178:181], v[232:235], v[66:69]
	s_setprio 0
	s_barrier
; #define PG8_STAGE(bufoff, gbase, voff) do { _Pragma("unroll") for (int _i = 0; _i < 2; ++_i) \
;         __builtin_amdgcn_global_load_lds((const unsigned*)((const char*)(gbase) + (voff)[_i]), (PG8_LAS unsigned*)(lds + (bufoff) + ldsw + _i * 8192), 16, 0, 0); } while (0)
; #define PG8_LDA(dst, b, h) do { _Pragma("unroll") for (int m = 0; m < 4; ++m) _Pragma("unroll") for (int k = 0; k < 2; ++k) dst[m][k] = *(const PG8_LAS bf16x8*)(lds + PG8_SA(b, h) + aoff + m * 2048 + k * 1024); } while (0)
; #define PG8_MMA(ai, bj, At, Bt) do { __builtin_amdgcn_s_setprio(1); _Pragma("unroll") for (int m = 0; m < 4; ++m) _Pragma("unroll") for (int n = 0; n < 2; ++n) _Pragma("unroll") for (int k = 0; k < 2; ++k) \
;         acc[ai][bj][m][n] = __builtin_amdgcn_mfma_f32_16x16x32_bf16(Bt[n][k], At[m][k], acc[ai][bj][m][n], 0, 0, 0); __builtin_amdgcn_s_setprio(0); } while (0)
; #define PG8_WAIT_V(n) asm volatile("s_waitcnt vmcnt(" #n ")" ::: "memory")
; #define PG8_WAIT_L(n) asm volatile("s_waitcnt lgkmcnt(" #n ")" ::: "memory")
; #define PG8_BAR __builtin_amdgcn_s_barrier()
; #define PG8_SCHED __builtin_amdgcn_sched_barrier(0)
; template <class Epi, class Sched, bool ALIGN_EPI = false, bool SP2 = false>
; __device__ __forceinline__ void gemm_phase(PG8_LAS unsigned char* lds, const Gemm g, const Sched& S, const Epi& E) {
;     ...
;         PG8_STAGE(PG8_SB(0, 0), cB, voffB); PG8_STAGE(PG8_SB(0, 1), cB + hstep, voffB); PG8_STAGE(PG8_SA(0, 0), cA, voffA); PG8_STAGE(PG8_SA(0, 1), cA + hstep, voffA);
;         if (wr == 1) PG8_BAR;
;         PG8_WAIT_V(2); PG8_BAR;
;         PG8_STAGE(PG8_SB(1, 0), cB + kstep, voffB); PG8_STAGE(PG8_SA(1, 0), cA + kstep, voffA); PG8_STAGE(PG8_SB(1, 1), cB + hstep + kstep, voffB);
;         PG8_WAIT_V(6); PG8_BAR;
;     ...
;             PG8_LDA(At, 1, 1); PG8_STAGE(PG8_SB(1, 0), b3, voffB); PG8_STAGE(PG8_SB(1, 1), b3 + hstep, voffB); PG8_STAGE(PG8_SA(1, 0), a3, voffA);
;             PG8_WAIT_V(8); PG8_WAIT_L(0); PG8_BAR; PG8_MMA(1, 0, At, B0); PG8_MMA(1, 1, At, B1); PG8_BAR; PG8_SCHED;
	s_add_i32 s59, s59, s93
	v_lshl_add_u64 v[136:137], v[136:137], 0, s[66:67]
	s_mov_b32 m0, s59
	ds_read_b128 v[202:205], v165 offset:49152
	ds_read_b128 v[208:211], v165 offset:50176
	ds_read_b128 v[212:215], v165 offset:51200
	ds_read_b128 v[216:219], v165 offset:52224
	ds_read_b128 v[220:223], v165 offset:53248
	ds_read_b128 v[224:227], v165 offset:54272
	ds_read_b128 v[228:231], v165 offset:55296
	ds_read_b128 v[232:235], v165 offset:56320
	global_load_lds_dwordx4 v[136:137], off
	v_lshl_add_u64 v[136:137], v[144:145], 0, s[66:67]
	s_add_i32 m0, s59, 0x2000
	s_add_i32 s59, s83, s93
	global_load_lds_dwordx4 v[136:137], off
	v_lshl_add_u64 v[136:137], v[182:183], 0, s[66:67]
	s_mov_b32 m0, s59
	s_nop 0
	global_load_lds_dwordx4 v[136:137], off
	v_lshl_add_u64 v[136:137], v[236:237], 0, s[66:67]
	s_add_i32 m0, s59, 0x2000
	s_nop 0
	global_load_lds_dwordx4 v[136:137], off
	v_lshl_add_u64 v[136:137], v[238:239], 0, s[66:67]
	s_mov_b32 m0, s73
	s_nop 0
	global_load_lds_dwordx4 v[136:137], off
	v_lshl_add_u64 v[136:137], v[240:241], 0, s[66:67]
	s_mov_b32 m0, s50
	s_nop 0
	global_load_lds_dwordx4 v[136:137], off
	s_waitcnt vmcnt(8)
	s_waitcnt lgkmcnt(0)
	s_barrier
	s_setprio 1
	s_waitcnt lgkmcnt(0)
	v_mfma_f32_16x16x32_bf16 v[62:65], v[148:151], v[202:205], v[62:65]
	v_mfma_f32_16x16x32_bf16 v[58:61], v[156:159], v[202:205], v[58:61]
	v_mfma_f32_16x16x32_bf16 v[46:49], v[148:151], v[212:215], v[46:49]
	v_mfma_f32_16x16x32_bf16 v[42:45], v[156:159], v[212:215], v[42:45]
	v_mfma_f32_16x16x32_bf16 v[30:33], v[148:151], v[220:223], v[30:33]
	v_mfma_f32_16x16x32_bf16 v[26:29], v[156:159], v[220:223], v[26:29]
	v_mfma_f32_16x16x32_bf16 v[14:17], v[148:151], v[228:231], v[14:17]
	v_mfma_f32_16x16x32_bf16 v[10:13], v[156:159], v[228:231], v[10:13]
	v_mfma_f32_16x16x32_bf16 v[62:65], v[152:155], v[208:211], v[62:65]
	v_mfma_f32_16x16x32_bf16 v[58:61], v[160:163], v[208:211], v[58:61]
	v_mfma_f32_16x16x32_bf16 v[46:49], v[152:155], v[216:219], v[46:49]
	v_mfma_f32_16x16x32_bf16 v[42:45], v[160:163], v[216:219], v[42:45]
	v_mfma_f32_16x16x32_bf16 v[30:33], v[152:155], v[224:227], v[30:33]
	v_mfma_f32_16x16x32_bf16 v[26:29], v[160:163], v[224:227], v[26:29]
	v_mfma_f32_16x16x32_bf16 v[14:17], v[152:155], v[232:235], v[14:17]
	v_mfma_f32_16x16x32_bf16 v[10:13], v[160:163], v[232:235], v[10:13]
	s_setprio 0
	s_setprio 1
	v_mfma_f32_16x16x32_bf16 v[54:57], v[166:169], v[202:205], v[54:57]
	v_mfma_f32_16x16x32_bf16 v[50:53], v[174:177], v[202:205], v[50:53]
	v_mfma_f32_16x16x32_bf16 v[38:41], v[166:169], v[212:215], v[38:41]
	v_mfma_f32_16x16x32_bf16 v[34:37], v[174:177], v[212:215], v[34:37]
	v_mfma_f32_16x16x32_bf16 v[22:25], v[166:169], v[220:223], v[22:25]
	v_mfma_f32_16x16x32_bf16 v[18:21], v[174:177], v[220:223], v[18:21]
	v_mfma_f32_16x16x32_bf16 v[6:9], v[166:169], v[228:231], v[6:9]
	v_mfma_f32_16x16x32_bf16 v[2:5], v[174:177], v[228:231], v[2:5]
	v_mfma_f32_16x16x32_bf16 v[54:57], v[170:173], v[208:211], v[54:57]
	v_mfma_f32_16x16x32_bf16 v[50:53], v[178:181], v[208:211], v[50:53]
	v_mfma_f32_16x16x32_bf16 v[38:41], v[170:173], v[216:219], v[38:41]
	v_mfma_f32_16x16x32_bf16 v[34:37], v[178:181], v[216:219], v[34:37]
	v_mfma_f32_16x16x32_bf16 v[22:25], v[170:173], v[224:227], v[22:25]
	v_mfma_f32_16x16x32_bf16 v[18:21], v[178:181], v[224:227], v[18:21]
	v_mfma_f32_16x16x32_bf16 v[6:9], v[170:173], v[232:235], v[6:9]
	v_mfma_f32_16x16x32_bf16 v[2:5], v[178:181], v[232:235], v[2:5]
	s_setprio 0
	s_barrier
	s_add_u32 s48, s48, 0x100
	s_addc_u32 s49, s49, 0
	s_add_u32 s80, s80, 0x100
	s_addc_u32 s81, s81, 0
	s_cmp_ge_u32 s82, s79
	s_mov_b32 s76, s82
	s_cbranch_scc0 .LBB0_849
	s_branch .Lkq_exit
	s_nop 0
	s_nop 0
	s_nop 0
	s_nop 0
.Lkq_1:
	s_waitcnt vmcnt(0)
	s_barrier
	s_mov_b64 s[76:77], s[48:49]
	s_add_u32 vcc_lo, s80, 0xffffff80
	s_addc_u32 vcc_hi, s81, -1
	s_add_u32 s76, s76, 0x80
	s_addc_u32 s77, s77, 0
	s_add_u32 vcc_lo, vcc_lo, 0x80
	s_addc_u32 vcc_hi, vcc_hi, 0
	v_lshl_add_u64 v[136:137], s[76:77], 0, v[0:1]
	s_add_i32 m0, s94, 0x4000
	v_lshl_add_u64 v[144:145], s[76:77], 0, v[130:131]
	global_load_lds_dwordx4 v[136:137], off
	s_add_i32 m0, s94, 0x6000
	s_nop 0
	global_load_lds_dwordx4 v[144:145], off
	v_lshl_add_u64 v[182:183], vcc, 0, v[0:1]
	s_add_i32 m0, s93, 0x14000
	v_lshl_add_u64 v[236:237], vcc, 0, v[130:131]
	global_load_lds_dwordx4 v[182:183], off
	s_add_i32 m0, s93, 0x16000
	s_nop 0
	global_load_lds_dwordx4 v[236:237], off
	s_add_u32 s76, s76, 0x80
	s_addc_u32 s77, s77, 0
	s_add_u32 vcc_lo, vcc_lo, 0x80
	s_addc_u32 vcc_hi, vcc_hi, 0
	s_mov_b32 s82, 3
	s_add_i32 s59, s79, -1
